# same as the peeled/sunk version but with the baseline's half-line GEMM staging layout (full-line staging off) to isolate its effect
# baseline (speedup 1.0000x reference)
.LBB0_214:
	s_add_u32 s24, s24, 0x40080
	s_addc_u32 s25, s25, 0
	s_add_u32 s48, s26, 0x100
	s_addc_u32 s49, s27, 0
	s_mov_b32 s50, -2
	s_waitcnt lgkmcnt(0)
	ds_read_b128 v[144:147], v151
	ds_read_b128 v[154:157], v151 offset:1024
	ds_read_b128 v[158:161], v151 offset:2048
	ds_read_b128 v[162:165], v151 offset:3072
	ds_read_b128 v[166:169], v152
	ds_read_b128 v[170:173], v152 offset:1024
	ds_read_b128 v[174:177], v152 offset:2048
	ds_read_b128 v[178:181], v152 offset:3072
	s_add_u32 s26, s24, 0xfffc0080
	s_addc_u32 s27, s25, -1
	s_cmp_eq_u32 s50, 12
	s_cselect_b32 s29, s17, s27
	s_cselect_b32 s28, s46, s26
	s_cselect_b32 s27, s15, s49
	s_cselect_b32 s26, s47, s48
	v_lshl_add_u64 v[214:215], s[24:25], 0, v[136:137]
	s_add_i32 m0, s23, 0xc000
	ds_read_b128 v[182:185], v153
	ds_read_b128 v[186:189], v153 offset:1024
	ds_read_b128 v[190:193], v153 offset:2048
	ds_read_b128 v[194:197], v153 offset:3072
	ds_read_b128 v[198:201], v153 offset:4096
	ds_read_b128 v[202:205], v153 offset:5120
	ds_read_b128 v[206:209], v153 offset:6144
	ds_read_b128 v[210:213], v153 offset:7168
	global_load_lds_dwordx4 v[214:215], off
	v_lshl_add_u64 v[214:215], s[24:25], 0, v[138:139]
	s_add_i32 m0, s23, 0xe000
	s_nop 0
	global_load_lds_dwordx4 v[214:215], off
	s_waitcnt vmcnt(8)
	s_waitcnt lgkmcnt(0)
	s_barrier
	s_setprio 0
	s_waitcnt lgkmcnt(0)
	v_mfma_f32_16x16x32_bf16 v[124:127], v[144:147], v[182:185], 0
	s_add_i32 s37, s37, 1
	s_mul_i32 s6, s37, s38
	s_mul_hi_u32 s7, s37, s41
	v_mfma_f32_16x16x32_bf16 v[120:123], v[158:161], v[182:185], 0
	s_add_i32 s7, s7, s6
	s_mul_i32 s6, s37, s41
	s_add_u32 s18, s6, s96
	v_mfma_f32_16x16x32_bf16 v[108:111], v[144:147], v[190:193], 0
	s_addc_u32 s19, s7, s31
	v_cmp_lt_i64_e64 s[6:7], s[18:19], v[140:141]
	s_ashr_i32 s14, s18, 31
	v_mfma_f32_16x16x32_bf16 v[104:107], v[158:161], v[190:193], 0
	s_lshr_b32 s14, s14, 29
	s_add_i32 s14, s18, s14
	s_ashr_i32 s15, s14, 3
	v_mfma_f32_16x16x32_bf16 v[92:95], v[144:147], v[198:201], 0
	s_and_b32 s14, s14, -8
	s_sub_i32 s14, s18, s14
	s_cmp_lt_i32 s14, 0
	v_mfma_f32_16x16x32_bf16 v[88:91], v[158:161], v[198:201], 0
	s_cselect_b32 s16, s33, 0x160
	s_mul_i32 s14, s14, s16
	s_add_i32 s14, s14, s15
	v_mfma_f32_16x16x32_bf16 v[76:79], v[144:147], v[206:209], 0
	s_mul_hi_i32 s15, s14, 0x2e8ba2e9
	s_lshr_b32 s16, s15, 31
	s_ashr_i32 s15, s15, 5
	v_mfma_f32_16x16x32_bf16 v[72:75], v[158:161], v[206:209], 0
	s_add_i32 s15, s15, s16
	s_lshl_b32 s16, s15, 3
	s_sub_i32 s17, 0x80, s16
	v_mfma_f32_16x16x32_bf16 v[124:127], v[154:157], v[186:189], v[124:127]
	s_min_i32 s17, s17, 8
	s_abs_i32 s18, s17
	v_cvt_f32_u32_e32 v252, s18
	v_mfma_f32_16x16x32_bf16 v[120:123], v[162:165], v[186:189], v[120:123]
	s_sub_i32 s20, 0, s18
	s_mulk_i32 s15, 0xb0
	s_sub_i32 s15, s14, s15
	v_mfma_f32_16x16x32_bf16 v[108:111], v[154:157], v[194:197], v[108:111]
	v_rcp_iflag_f32_e32 v252, v252
	s_abs_i32 s14, s15
	s_xor_b32 s19, s15, s17
	v_mfma_f32_16x16x32_bf16 v[104:107], v[162:165], v[194:197], v[104:107]
	s_ashr_i32 s19, s19, 31
	v_mul_f32_e32 v252, 0x4f7ffffe, v252
	v_cvt_u32_f32_e32 v252, v252
	v_mfma_f32_16x16x32_bf16 v[92:95], v[154:157], v[202:205], v[92:95]
	s_nop 0
	v_readfirstlane_b32 s21, v252
	s_mul_i32 s20, s20, s21
	v_mfma_f32_16x16x32_bf16 v[88:91], v[162:165], v[202:205], v[88:91]
	s_mul_hi_u32 s20, s21, s20
	s_add_i32 s21, s21, s20
	s_mul_hi_u32 s20, s14, s21
	v_mfma_f32_16x16x32_bf16 v[76:79], v[154:157], v[210:213], v[76:79]
	s_mul_i32 s21, s20, s18
	s_sub_i32 s14, s14, s21
	s_add_i32 s98, s20, 1
	v_mfma_f32_16x16x32_bf16 v[72:75], v[162:165], v[210:213], v[72:75]
	s_sub_i32 s21, s14, s18
	s_cmp_ge_u32 s14, s18
	s_cselect_b32 s20, s98, s20
	s_setprio 0
	s_setprio 0
	v_mfma_f32_16x16x32_bf16 v[116:119], v[166:169], v[182:185], 0
	s_cselect_b32 s14, s21, s14
	s_add_i32 s21, s20, 1
	s_cmp_ge_u32 s14, s18
	v_mfma_f32_16x16x32_bf16 v[112:115], v[174:177], v[182:185], 0
	s_cselect_b32 s14, s21, s20
	s_xor_b32 s14, s14, s19
	s_sub_i32 s14, s14, s19
	v_mfma_f32_16x16x32_bf16 v[100:103], v[166:169], v[190:193], 0
	s_mul_i32 s17, s14, s17
	s_sub_i32 s15, s15, s17
	s_add_i32 s16, s16, s15
	v_mfma_f32_16x16x32_bf16 v[96:99], v[174:177], v[190:193], 0
	s_ashr_i32 s17, s16, 31
	s_lshl_b64 s[18:19], s[16:17], 19
	s_add_u32 s18, s90, s18
	v_mfma_f32_16x16x32_bf16 v[84:87], v[166:169], v[198:201], 0
	s_addc_u32 s19, s91, s19
	s_and_b64 s[20:21], s[6:7], exec
	s_cselect_b32 s17, s19, s25
	v_mfma_f32_16x16x32_bf16 v[80:83], v[174:177], v[198:201], 0
	s_cselect_b32 s46, s18, s24
	s_ashr_i32 s15, s14, 31
	s_lshl_b64 s[20:21], s[14:15], 19
	v_mfma_f32_16x16x32_bf16 v[68:71], v[166:169], v[206:209], 0
	s_add_u32 s20, s2, s20
	s_addc_u32 s21, s3, s21
	s_and_b64 s[98:99], s[6:7], exec
	v_mfma_f32_16x16x32_bf16 v[64:67], v[174:177], v[206:209], 0
	s_cselect_b32 s15, s21, s27
	s_cselect_b32 s47, s20, s26
	v_mfma_f32_16x16x32_bf16 v[116:119], v[170:173], v[186:189], v[116:119]
	v_mfma_f32_16x16x32_bf16 v[112:115], v[178:181], v[186:189], v[112:115]
	v_mfma_f32_16x16x32_bf16 v[100:103], v[170:173], v[194:197], v[100:103]
	v_mfma_f32_16x16x32_bf16 v[96:99], v[178:181], v[194:197], v[96:99]
	v_mfma_f32_16x16x32_bf16 v[84:87], v[170:173], v[202:205], v[84:87]
	v_mfma_f32_16x16x32_bf16 v[80:83], v[178:181], v[202:205], v[80:83]
	v_mfma_f32_16x16x32_bf16 v[68:71], v[170:173], v[210:213], v[68:71]
	v_mfma_f32_16x16x32_bf16 v[64:67], v[178:181], v[210:213], v[64:67]
	s_setprio 0
	s_barrier
	s_add_i32 s51, s42, s30
	v_lshl_add_u64 v[214:215], s[26:27], 0, v[132:133]
	s_mov_b32 m0, s51
	ds_read_b128 v[182:185], v153 offset:16384
	ds_read_b128 v[186:189], v153 offset:17408
	ds_read_b128 v[190:193], v153 offset:18432
	ds_read_b128 v[194:197], v153 offset:19456
	ds_read_b128 v[198:201], v153 offset:20480
	ds_read_b128 v[202:205], v153 offset:21504
	ds_read_b128 v[206:209], v153 offset:22528
	ds_read_b128 v[210:213], v153 offset:23552
	global_load_lds_dwordx4 v[214:215], off
	s_add_i32 m0, s51, 0x2000
	s_add_u32 s52, s26, 0x40000
	v_lshl_add_u64 v[216:217], s[26:27], 0, v[128:129]
	s_addc_u32 s53, s27, 0
	s_add_i32 s51, s43, s30
	global_load_lds_dwordx4 v[216:217], off
	v_lshl_add_u64 v[218:219], s[52:53], 0, v[132:133]
	s_mov_b32 m0, s51
	v_lshl_add_u64 v[220:221], s[28:29], 0, v[130:131]
	global_load_lds_dwordx4 v[218:219], off
	v_lshl_add_u64 v[218:219], s[52:53], 0, v[128:129]
	s_add_i32 m0, s51, 0x2000
	s_nop 0
	global_load_lds_dwordx4 v[218:219], off
	v_lshl_add_u64 v[218:219], s[28:29], 0, v[134:135]
	s_mov_b32 m0, s23
	s_nop 0
	global_load_lds_dwordx4 v[218:219], off
	s_mov_b32 m0, s34
	s_nop 0
	global_load_lds_dwordx4 v[220:221], off
	s_waitcnt vmcnt(8)
	s_waitcnt lgkmcnt(0)
	s_barrier
	s_setprio 0
	s_waitcnt lgkmcnt(0)
	v_mfma_f32_16x16x32_bf16 v[60:63], v[144:147], v[182:185], 0
	v_mfma_f32_16x16x32_bf16 v[56:59], v[158:161], v[182:185], 0
	v_mfma_f32_16x16x32_bf16 v[44:47], v[144:147], v[190:193], 0
	v_mfma_f32_16x16x32_bf16 v[40:43], v[158:161], v[190:193], 0
	v_mfma_f32_16x16x32_bf16 v[28:31], v[144:147], v[198:201], 0
	v_mfma_f32_16x16x32_bf16 v[24:27], v[158:161], v[198:201], 0
	v_mfma_f32_16x16x32_bf16 v[12:15], v[144:147], v[206:209], 0
	v_mfma_f32_16x16x32_bf16 v[8:11], v[158:161], v[206:209], 0
	v_mfma_f32_16x16x32_bf16 v[60:63], v[154:157], v[186:189], v[60:63]
	v_mfma_f32_16x16x32_bf16 v[56:59], v[162:165], v[186:189], v[56:59]
	v_mfma_f32_16x16x32_bf16 v[44:47], v[154:157], v[194:197], v[44:47]
	v_mfma_f32_16x16x32_bf16 v[40:43], v[162:165], v[194:197], v[40:43]
	v_mfma_f32_16x16x32_bf16 v[28:31], v[154:157], v[202:205], v[28:31]
	v_mfma_f32_16x16x32_bf16 v[24:27], v[162:165], v[202:205], v[24:27]
	v_mfma_f32_16x16x32_bf16 v[12:15], v[154:157], v[210:213], v[12:15]
	v_mfma_f32_16x16x32_bf16 v[8:11], v[162:165], v[210:213], v[8:11]
	s_setprio 0
	s_setprio 0
	v_mfma_f32_16x16x32_bf16 v[52:55], v[166:169], v[182:185], 0
	v_mfma_f32_16x16x32_bf16 v[48:51], v[174:177], v[182:185], 0
	v_mfma_f32_16x16x32_bf16 v[36:39], v[166:169], v[190:193], 0
	v_mfma_f32_16x16x32_bf16 v[32:35], v[174:177], v[190:193], 0
	v_mfma_f32_16x16x32_bf16 v[20:23], v[166:169], v[198:201], 0
	v_mfma_f32_16x16x32_bf16 v[16:19], v[174:177], v[198:201], 0
	v_mfma_f32_16x16x32_bf16 v[4:7], v[166:169], v[206:209], 0
	v_mfma_f32_16x16x32_bf16 v[0:3], v[174:177], v[206:209], 0
	v_mfma_f32_16x16x32_bf16 v[52:55], v[170:173], v[186:189], v[52:55]
	v_mfma_f32_16x16x32_bf16 v[48:51], v[178:181], v[186:189], v[48:51]
	v_mfma_f32_16x16x32_bf16 v[36:39], v[170:173], v[194:197], v[36:39]
	v_mfma_f32_16x16x32_bf16 v[32:35], v[178:181], v[194:197], v[32:35]
	v_mfma_f32_16x16x32_bf16 v[20:23], v[170:173], v[202:205], v[20:23]
	v_mfma_f32_16x16x32_bf16 v[16:19], v[178:181], v[202:205], v[16:19]
	v_mfma_f32_16x16x32_bf16 v[4:7], v[170:173], v[210:213], v[4:7]
	v_mfma_f32_16x16x32_bf16 v[0:3], v[178:181], v[210:213], v[0:3]
	s_setprio 0
	s_barrier
	s_add_i32 s51, 0, 0x18000
	s_add_i32 s52, 0, 0x1c000
	v_add_u32_e32 v162, s51, v149
	v_add_u32_e32 v178, s52, v149
	ds_read_b128 v[144:147], v162
	ds_read_b128 v[154:157], v162 offset:1024
	ds_read_b128 v[158:161], v162 offset:2048
	ds_read_b128 v[162:165], v162 offset:3072
	ds_read_b128 v[166:169], v178
	ds_read_b128 v[170:173], v178 offset:1024
	ds_read_b128 v[174:177], v178 offset:2048
	ds_read_b128 v[178:181], v178 offset:3072
	s_add_u32 s28, s28, 0x40000
	s_addc_u32 s29, s29, 0
	s_mov_b32 m0, s35
	v_lshl_add_u64 v[222:223], s[28:29], 0, v[134:135]
	ds_read_b128 v[182:185], v153 offset:32768
	ds_read_b128 v[186:189], v153 offset:33792
	ds_read_b128 v[190:193], v153 offset:34816
	ds_read_b128 v[194:197], v153 offset:35840
	ds_read_b128 v[198:201], v153 offset:36864
	ds_read_b128 v[202:205], v153 offset:37888
	ds_read_b128 v[206:209], v153 offset:38912
	ds_read_b128 v[210:213], v153 offset:39936
	global_load_lds_dwordx4 v[222:223], off
	v_lshl_add_u64 v[222:223], s[28:29], 0, v[130:131]
	s_mov_b32 m0, s36
	s_nop 0
	global_load_lds_dwordx4 v[222:223], off
	s_waitcnt vmcnt(8)
	s_waitcnt lgkmcnt(0)
	s_barrier
	s_setprio 0
	s_waitcnt lgkmcnt(0)
	v_mfma_f32_16x16x32_bf16 v[124:127], v[144:147], v[182:185], v[124:127]
	v_mfma_f32_16x16x32_bf16 v[120:123], v[158:161], v[182:185], v[120:123]
	v_mfma_f32_16x16x32_bf16 v[108:111], v[144:147], v[190:193], v[108:111]
	v_mfma_f32_16x16x32_bf16 v[104:107], v[158:161], v[190:193], v[104:107]
	v_mfma_f32_16x16x32_bf16 v[92:95], v[144:147], v[198:201], v[92:95]
	v_mfma_f32_16x16x32_bf16 v[88:91], v[158:161], v[198:201], v[88:91]
	v_mfma_f32_16x16x32_bf16 v[76:79], v[144:147], v[206:209], v[76:79]
	v_mfma_f32_16x16x32_bf16 v[72:75], v[158:161], v[206:209], v[72:75]
	v_mfma_f32_16x16x32_bf16 v[124:127], v[154:157], v[186:189], v[124:127]
	v_mfma_f32_16x16x32_bf16 v[120:123], v[162:165], v[186:189], v[120:123]
	v_mfma_f32_16x16x32_bf16 v[108:111], v[154:157], v[194:197], v[108:111]
	v_mfma_f32_16x16x32_bf16 v[104:107], v[162:165], v[194:197], v[104:107]
	v_mfma_f32_16x16x32_bf16 v[92:95], v[154:157], v[202:205], v[92:95]
	v_mfma_f32_16x16x32_bf16 v[88:91], v[162:165], v[202:205], v[88:91]
	v_mfma_f32_16x16x32_bf16 v[76:79], v[154:157], v[210:213], v[76:79]
	v_mfma_f32_16x16x32_bf16 v[72:75], v[162:165], v[210:213], v[72:75]
	s_setprio 0
	s_setprio 0
	v_mfma_f32_16x16x32_bf16 v[116:119], v[166:169], v[182:185], v[116:119]
	v_mfma_f32_16x16x32_bf16 v[112:115], v[174:177], v[182:185], v[112:115]
	v_mfma_f32_16x16x32_bf16 v[100:103], v[166:169], v[190:193], v[100:103]
	v_mfma_f32_16x16x32_bf16 v[96:99], v[174:177], v[190:193], v[96:99]
	v_mfma_f32_16x16x32_bf16 v[84:87], v[166:169], v[198:201], v[84:87]
	v_mfma_f32_16x16x32_bf16 v[80:83], v[174:177], v[198:201], v[80:83]
	v_mfma_f32_16x16x32_bf16 v[68:71], v[166:169], v[206:209], v[68:71]
	v_mfma_f32_16x16x32_bf16 v[64:67], v[174:177], v[206:209], v[64:67]
	v_mfma_f32_16x16x32_bf16 v[116:119], v[170:173], v[186:189], v[116:119]
	v_mfma_f32_16x16x32_bf16 v[112:115], v[178:181], v[186:189], v[112:115]
	v_mfma_f32_16x16x32_bf16 v[100:103], v[170:173], v[194:197], v[100:103]
	v_mfma_f32_16x16x32_bf16 v[96:99], v[178:181], v[194:197], v[96:99]
	v_mfma_f32_16x16x32_bf16 v[84:87], v[170:173], v[202:205], v[84:87]
	v_mfma_f32_16x16x32_bf16 v[80:83], v[178:181], v[202:205], v[80:83]
	v_mfma_f32_16x16x32_bf16 v[68:71], v[170:173], v[210:213], v[68:71]
	v_mfma_f32_16x16x32_bf16 v[64:67], v[178:181], v[210:213], v[64:67]
	s_setprio 0
	s_barrier
	s_add_i32 s28, s51, s30
	v_lshl_add_u64 v[214:215], v[214:215], 0, s[10:11]
	s_mov_b32 m0, s28
	ds_read_b128 v[182:185], v153 offset:49152
	ds_read_b128 v[186:189], v153 offset:50176
	ds_read_b128 v[190:193], v153 offset:51200
	ds_read_b128 v[194:197], v153 offset:52224
	ds_read_b128 v[198:201], v153 offset:53248
	ds_read_b128 v[202:205], v153 offset:54272
	ds_read_b128 v[206:209], v153 offset:55296
	ds_read_b128 v[210:213], v153 offset:56320
	global_load_lds_dwordx4 v[214:215], off
	s_add_i32 m0, s28, 0x2000
	s_add_u32 s26, s26, 0x40080
	v_lshl_add_u64 v[214:215], v[216:217], 0, s[10:11]
	s_addc_u32 s27, s27, 0
	s_add_i32 s28, s52, s30
	global_load_lds_dwordx4 v[214:215], off
	v_lshl_add_u64 v[214:215], s[26:27], 0, v[132:133]
	s_mov_b32 m0, s28
	s_nop 0
	global_load_lds_dwordx4 v[214:215], off
	v_lshl_add_u64 v[214:215], s[26:27], 0, v[128:129]
	s_add_i32 m0, s28, 0x2000
	s_nop 0
	global_load_lds_dwordx4 v[214:215], off
	v_lshl_add_u64 v[214:215], v[218:219], 0, s[10:11]
	s_mov_b32 m0, s39
	s_nop 0
	global_load_lds_dwordx4 v[214:215], off
	v_lshl_add_u64 v[214:215], v[220:221], 0, s[10:11]
	s_mov_b32 m0, s40
	s_nop 0
	global_load_lds_dwordx4 v[214:215], off
	s_waitcnt vmcnt(8)
	s_waitcnt lgkmcnt(0)
	s_barrier
	s_setprio 0
	s_waitcnt lgkmcnt(0)
	v_mfma_f32_16x16x32_bf16 v[60:63], v[144:147], v[182:185], v[60:63]
	v_mfma_f32_16x16x32_bf16 v[56:59], v[158:161], v[182:185], v[56:59]
	v_mfma_f32_16x16x32_bf16 v[44:47], v[144:147], v[190:193], v[44:47]
	v_mfma_f32_16x16x32_bf16 v[40:43], v[158:161], v[190:193], v[40:43]
	v_mfma_f32_16x16x32_bf16 v[28:31], v[144:147], v[198:201], v[28:31]
	v_mfma_f32_16x16x32_bf16 v[24:27], v[158:161], v[198:201], v[24:27]
	v_mfma_f32_16x16x32_bf16 v[12:15], v[144:147], v[206:209], v[12:15]
	v_mfma_f32_16x16x32_bf16 v[8:11], v[158:161], v[206:209], v[8:11]
	v_mfma_f32_16x16x32_bf16 v[60:63], v[154:157], v[186:189], v[60:63]
	v_mfma_f32_16x16x32_bf16 v[56:59], v[162:165], v[186:189], v[56:59]
	v_mfma_f32_16x16x32_bf16 v[44:47], v[154:157], v[194:197], v[44:47]
	v_mfma_f32_16x16x32_bf16 v[40:43], v[162:165], v[194:197], v[40:43]
	v_mfma_f32_16x16x32_bf16 v[28:31], v[154:157], v[202:205], v[28:31]
	v_mfma_f32_16x16x32_bf16 v[24:27], v[162:165], v[202:205], v[24:27]
	v_mfma_f32_16x16x32_bf16 v[12:15], v[154:157], v[210:213], v[12:15]
	v_mfma_f32_16x16x32_bf16 v[8:11], v[162:165], v[210:213], v[8:11]
	s_setprio 0
	s_setprio 0
	v_mfma_f32_16x16x32_bf16 v[52:55], v[166:169], v[182:185], v[52:55]
	v_mfma_f32_16x16x32_bf16 v[48:51], v[174:177], v[182:185], v[48:51]
	v_mfma_f32_16x16x32_bf16 v[36:39], v[166:169], v[190:193], v[36:39]
	v_mfma_f32_16x16x32_bf16 v[32:35], v[174:177], v[190:193], v[32:35]
	v_mfma_f32_16x16x32_bf16 v[20:23], v[166:169], v[198:201], v[20:23]
	v_mfma_f32_16x16x32_bf16 v[16:19], v[174:177], v[198:201], v[16:19]
	v_mfma_f32_16x16x32_bf16 v[4:7], v[166:169], v[206:209], v[4:7]
	v_mfma_f32_16x16x32_bf16 v[0:3], v[174:177], v[206:209], v[0:3]
	v_mfma_f32_16x16x32_bf16 v[52:55], v[170:173], v[186:189], v[52:55]
	v_mfma_f32_16x16x32_bf16 v[48:51], v[178:181], v[186:189], v[48:51]
	v_mfma_f32_16x16x32_bf16 v[36:39], v[170:173], v[194:197], v[36:39]
	v_mfma_f32_16x16x32_bf16 v[32:35], v[178:181], v[194:197], v[32:35]
	v_mfma_f32_16x16x32_bf16 v[20:23], v[170:173], v[202:205], v[20:23]
	v_mfma_f32_16x16x32_bf16 v[16:19], v[178:181], v[202:205], v[16:19]
	v_mfma_f32_16x16x32_bf16 v[4:7], v[170:173], v[210:213], v[4:7]
	v_mfma_f32_16x16x32_bf16 v[0:3], v[178:181], v[210:213], v[0:3]
	s_setprio 0
	s_barrier
	s_add_i32 s50, s50, 2
	s_add_u32 s24, s24, 0x100
	s_addc_u32 s25, s25, 0
	s_add_u32 s48, s48, 0x100
	s_addc_u32 s49, s49, 0
	s_cmp_gt_u32 s50, 13

.LBB0_295:
	s_add_u32 s46, s20, 0x100
	s_addc_u32 s47, s21, 0
	s_mov_b32 s48, -2
	s_waitcnt lgkmcnt(0)
	ds_read_b128 v[144:147], v169
	ds_read_b128 v[148:151], v169 offset:1024
	ds_read_b128 v[152:155], v169 offset:2048
	ds_read_b128 v[156:159], v169 offset:3072
	ds_read_b128 v[160:163], v170
	ds_read_b128 v[172:175], v170 offset:1024
	ds_read_b128 v[176:179], v170 offset:2048
	ds_read_b128 v[180:183], v170 offset:3072
	s_add_u32 s20, s18, 0x100
	s_addc_u32 s21, s19, 0
	s_cmp_eq_u32 s48, 40
	s_cselect_b32 s25, s9, s21
	s_cselect_b32 s24, s8, s20
	s_cselect_b32 s23, s17, s47
	s_cselect_b32 s22, s16, s46
	v_lshl_add_u64 v[164:165], s[18:19], 0, v[136:137]
	s_add_i32 m0, s28, 0xc000
	ds_read_b128 v[184:187], v171
	ds_read_b128 v[188:191], v171 offset:1024
	ds_read_b128 v[192:195], v171 offset:2048
	ds_read_b128 v[196:199], v171 offset:3072
	ds_read_b128 v[200:203], v171 offset:4096
	ds_read_b128 v[204:207], v171 offset:5120
	ds_read_b128 v[208:211], v171 offset:6144
	ds_read_b128 v[212:215], v171 offset:7168
	global_load_lds_dwordx4 v[164:165], off
	v_lshl_add_u64 v[164:165], s[18:19], 0, v[138:139]
	s_add_i32 m0, s28, 0xe000
	s_nop 0
	global_load_lds_dwordx4 v[164:165], off
	s_waitcnt vmcnt(8)
	s_waitcnt lgkmcnt(0)
	s_barrier
	s_setprio 0
	s_waitcnt lgkmcnt(0)
	v_mfma_f32_16x16x32_bf16 v[124:127], v[144:147], v[184:187], 0
	v_mfma_f32_16x16x32_bf16 v[120:123], v[152:155], v[184:187], 0
	v_mfma_f32_16x16x32_bf16 v[116:119], v[144:147], v[192:195], 0
	v_mfma_f32_16x16x32_bf16 v[112:115], v[152:155], v[192:195], 0
	v_mfma_f32_16x16x32_bf16 v[96:99], v[144:147], v[200:203], 0
	v_mfma_f32_16x16x32_bf16 v[88:91], v[152:155], v[200:203], 0
	v_mfma_f32_16x16x32_bf16 v[80:83], v[144:147], v[208:211], 0
	v_mfma_f32_16x16x32_bf16 v[72:75], v[152:155], v[208:211], 0
	v_mfma_f32_16x16x32_bf16 v[124:127], v[148:151], v[188:191], v[124:127]
	v_mfma_f32_16x16x32_bf16 v[120:123], v[156:159], v[188:191], v[120:123]
	v_mfma_f32_16x16x32_bf16 v[116:119], v[148:151], v[196:199], v[116:119]
	v_mfma_f32_16x16x32_bf16 v[112:115], v[156:159], v[196:199], v[112:115]
	v_mfma_f32_16x16x32_bf16 v[96:99], v[148:151], v[204:207], v[96:99]
	v_mfma_f32_16x16x32_bf16 v[88:91], v[156:159], v[204:207], v[88:91]
	v_mfma_f32_16x16x32_bf16 v[80:83], v[148:151], v[212:215], v[80:83]
	v_mfma_f32_16x16x32_bf16 v[72:75], v[156:159], v[212:215], v[72:75]
	s_setprio 0
	s_setprio 0
	v_mfma_f32_16x16x32_bf16 v[108:111], v[160:163], v[184:187], 0
	v_mfma_f32_16x16x32_bf16 v[104:107], v[176:179], v[184:187], 0
	v_mfma_f32_16x16x32_bf16 v[100:103], v[160:163], v[192:195], 0
	v_mfma_f32_16x16x32_bf16 v[92:95], v[176:179], v[192:195], 0
	v_mfma_f32_16x16x32_bf16 v[84:87], v[160:163], v[200:203], 0
	v_mfma_f32_16x16x32_bf16 v[76:79], v[176:179], v[200:203], 0
	v_mfma_f32_16x16x32_bf16 v[68:71], v[160:163], v[208:211], 0
	v_mfma_f32_16x16x32_bf16 v[64:67], v[176:179], v[208:211], 0
	v_mfma_f32_16x16x32_bf16 v[108:111], v[172:175], v[188:191], v[108:111]
	v_mfma_f32_16x16x32_bf16 v[104:107], v[180:183], v[188:191], v[104:107]
	v_mfma_f32_16x16x32_bf16 v[100:103], v[172:175], v[196:199], v[100:103]
	v_mfma_f32_16x16x32_bf16 v[92:95], v[180:183], v[196:199], v[92:95]
	v_mfma_f32_16x16x32_bf16 v[84:87], v[172:175], v[204:207], v[84:87]
	v_mfma_f32_16x16x32_bf16 v[76:79], v[180:183], v[204:207], v[76:79]
	v_mfma_f32_16x16x32_bf16 v[68:71], v[172:175], v[212:215], v[68:71]
	v_mfma_f32_16x16x32_bf16 v[64:67], v[180:183], v[212:215], v[64:67]
	s_setprio 0
	s_barrier
	s_add_i32 s18, s40, s26
	v_lshl_add_u64 v[164:165], s[22:23], 0, v[132:133]
	s_mov_b32 m0, s18
	ds_read_b128 v[184:187], v171 offset:16384
	ds_read_b128 v[188:191], v171 offset:17408
	ds_read_b128 v[192:195], v171 offset:18432
	ds_read_b128 v[196:199], v171 offset:19456
	ds_read_b128 v[200:203], v171 offset:20480
	ds_read_b128 v[204:207], v171 offset:21504
	ds_read_b128 v[208:211], v171 offset:22528
	ds_read_b128 v[212:215], v171 offset:23552
	global_load_lds_dwordx4 v[164:165], off
	s_add_i32 m0, s18, 0x2000
	s_add_u32 s18, s22, 0xb0000
	v_lshl_add_u64 v[216:217], s[22:23], 0, v[128:129]
	s_addc_u32 s19, s23, 0
	s_add_i32 s49, s41, s26
	global_load_lds_dwordx4 v[216:217], off
	v_lshl_add_u64 v[218:219], s[18:19], 0, v[132:133]
	s_mov_b32 m0, s49
	v_lshl_add_u64 v[220:221], s[24:25], 0, v[130:131]
	global_load_lds_dwordx4 v[218:219], off
	v_lshl_add_u64 v[218:219], s[18:19], 0, v[128:129]
	s_add_i32 m0, s49, 0x2000
	s_nop 0
	global_load_lds_dwordx4 v[218:219], off
	v_lshl_add_u64 v[218:219], s[24:25], 0, v[134:135]
	s_mov_b32 m0, s28
	s_nop 0
	global_load_lds_dwordx4 v[218:219], off
	s_mov_b32 m0, s29
	s_nop 0
	global_load_lds_dwordx4 v[220:221], off
	s_waitcnt vmcnt(8)
	s_waitcnt lgkmcnt(0)
	s_barrier
	s_setprio 0
	s_waitcnt lgkmcnt(0)
	v_mfma_f32_16x16x32_bf16 v[60:63], v[144:147], v[184:187], 0
	v_mfma_f32_16x16x32_bf16 v[56:59], v[152:155], v[184:187], 0
	v_mfma_f32_16x16x32_bf16 v[48:51], v[144:147], v[192:195], 0
	v_mfma_f32_16x16x32_bf16 v[40:43], v[152:155], v[192:195], 0
	v_mfma_f32_16x16x32_bf16 v[32:35], v[144:147], v[200:203], 0
	v_mfma_f32_16x16x32_bf16 v[24:27], v[152:155], v[200:203], 0
	v_mfma_f32_16x16x32_bf16 v[16:19], v[144:147], v[208:211], 0
	v_mfma_f32_16x16x32_bf16 v[8:11], v[152:155], v[208:211], 0
	v_mfma_f32_16x16x32_bf16 v[60:63], v[148:151], v[188:191], v[60:63]
	v_mfma_f32_16x16x32_bf16 v[56:59], v[156:159], v[188:191], v[56:59]
	v_mfma_f32_16x16x32_bf16 v[48:51], v[148:151], v[196:199], v[48:51]
	v_mfma_f32_16x16x32_bf16 v[40:43], v[156:159], v[196:199], v[40:43]
	v_mfma_f32_16x16x32_bf16 v[32:35], v[148:151], v[204:207], v[32:35]
	v_mfma_f32_16x16x32_bf16 v[24:27], v[156:159], v[204:207], v[24:27]
	v_mfma_f32_16x16x32_bf16 v[16:19], v[148:151], v[212:215], v[16:19]
	v_mfma_f32_16x16x32_bf16 v[8:11], v[156:159], v[212:215], v[8:11]
	s_setprio 0
	s_setprio 0
	v_mfma_f32_16x16x32_bf16 v[52:55], v[160:163], v[184:187], 0
	v_mfma_f32_16x16x32_bf16 v[44:47], v[176:179], v[184:187], 0
	v_mfma_f32_16x16x32_bf16 v[36:39], v[160:163], v[192:195], 0
	v_mfma_f32_16x16x32_bf16 v[28:31], v[176:179], v[192:195], 0
	v_mfma_f32_16x16x32_bf16 v[20:23], v[160:163], v[200:203], 0
	v_mfma_f32_16x16x32_bf16 v[12:15], v[176:179], v[200:203], 0
	v_mfma_f32_16x16x32_bf16 v[4:7], v[160:163], v[208:211], 0
	v_mfma_f32_16x16x32_bf16 v[0:3], v[176:179], v[208:211], 0
	v_mfma_f32_16x16x32_bf16 v[52:55], v[172:175], v[188:191], v[52:55]
	v_mfma_f32_16x16x32_bf16 v[44:47], v[180:183], v[188:191], v[44:47]
	v_mfma_f32_16x16x32_bf16 v[36:39], v[172:175], v[196:199], v[36:39]
	v_mfma_f32_16x16x32_bf16 v[28:31], v[180:183], v[196:199], v[28:31]
	v_mfma_f32_16x16x32_bf16 v[20:23], v[172:175], v[204:207], v[20:23]
	v_mfma_f32_16x16x32_bf16 v[12:15], v[180:183], v[204:207], v[12:15]
	v_mfma_f32_16x16x32_bf16 v[4:7], v[172:175], v[212:215], v[4:7]
	v_mfma_f32_16x16x32_bf16 v[0:3], v[180:183], v[212:215], v[0:3]
	s_setprio 0
	s_barrier
	s_add_i32 s49, 0, 0x18000
	s_add_i32 s50, 0, 0x1c000
	v_add_u32_e32 v156, s49, v167
	v_add_u32_e32 v180, s50, v167
	ds_read_b128 v[144:147], v156
	ds_read_b128 v[148:151], v156 offset:1024
	ds_read_b128 v[152:155], v156 offset:2048
	ds_read_b128 v[156:159], v156 offset:3072
	ds_read_b128 v[160:163], v180
	ds_read_b128 v[172:175], v180 offset:1024
	ds_read_b128 v[176:179], v180 offset:2048
	ds_read_b128 v[180:183], v180 offset:3072
	s_add_u32 s18, s24, 0xb0000
	s_addc_u32 s19, s25, 0
	s_mov_b32 m0, s30
	v_lshl_add_u64 v[222:223], s[18:19], 0, v[134:135]
	ds_read_b128 v[184:187], v171 offset:32768
	ds_read_b128 v[188:191], v171 offset:33792
	ds_read_b128 v[192:195], v171 offset:34816
	ds_read_b128 v[196:199], v171 offset:35840
	ds_read_b128 v[200:203], v171 offset:36864
	ds_read_b128 v[204:207], v171 offset:37888
	ds_read_b128 v[208:211], v171 offset:38912
	ds_read_b128 v[212:215], v171 offset:39936
	global_load_lds_dwordx4 v[222:223], off
	v_lshl_add_u64 v[222:223], s[18:19], 0, v[130:131]
	s_mov_b32 m0, s31
	s_nop 0
	global_load_lds_dwordx4 v[222:223], off
	s_waitcnt vmcnt(8)
	s_waitcnt lgkmcnt(0)
	s_barrier
	s_setprio 0
	s_waitcnt lgkmcnt(0)
	v_mfma_f32_16x16x32_bf16 v[124:127], v[144:147], v[184:187], v[124:127]
	v_mfma_f32_16x16x32_bf16 v[120:123], v[152:155], v[184:187], v[120:123]
	v_mfma_f32_16x16x32_bf16 v[116:119], v[144:147], v[192:195], v[116:119]
	v_mfma_f32_16x16x32_bf16 v[112:115], v[152:155], v[192:195], v[112:115]
	v_mfma_f32_16x16x32_bf16 v[96:99], v[144:147], v[200:203], v[96:99]
	v_mfma_f32_16x16x32_bf16 v[88:91], v[152:155], v[200:203], v[88:91]
	v_mfma_f32_16x16x32_bf16 v[80:83], v[144:147], v[208:211], v[80:83]
	v_mfma_f32_16x16x32_bf16 v[72:75], v[152:155], v[208:211], v[72:75]
	v_mfma_f32_16x16x32_bf16 v[124:127], v[148:151], v[188:191], v[124:127]
	v_mfma_f32_16x16x32_bf16 v[120:123], v[156:159], v[188:191], v[120:123]
	v_mfma_f32_16x16x32_bf16 v[116:119], v[148:151], v[196:199], v[116:119]
	v_mfma_f32_16x16x32_bf16 v[112:115], v[156:159], v[196:199], v[112:115]
	v_mfma_f32_16x16x32_bf16 v[96:99], v[148:151], v[204:207], v[96:99]
	v_mfma_f32_16x16x32_bf16 v[88:91], v[156:159], v[204:207], v[88:91]
	v_mfma_f32_16x16x32_bf16 v[80:83], v[148:151], v[212:215], v[80:83]
	v_mfma_f32_16x16x32_bf16 v[72:75], v[156:159], v[212:215], v[72:75]
	s_setprio 0
	s_setprio 0
	v_mfma_f32_16x16x32_bf16 v[108:111], v[160:163], v[184:187], v[108:111]
	v_mfma_f32_16x16x32_bf16 v[104:107], v[176:179], v[184:187], v[104:107]
	v_mfma_f32_16x16x32_bf16 v[100:103], v[160:163], v[192:195], v[100:103]
	v_mfma_f32_16x16x32_bf16 v[92:95], v[176:179], v[192:195], v[92:95]
	v_mfma_f32_16x16x32_bf16 v[84:87], v[160:163], v[200:203], v[84:87]
	v_mfma_f32_16x16x32_bf16 v[76:79], v[176:179], v[200:203], v[76:79]
	v_mfma_f32_16x16x32_bf16 v[68:71], v[160:163], v[208:211], v[68:71]
	v_mfma_f32_16x16x32_bf16 v[64:67], v[176:179], v[208:211], v[64:67]
	v_mfma_f32_16x16x32_bf16 v[108:111], v[172:175], v[188:191], v[108:111]
	v_mfma_f32_16x16x32_bf16 v[104:107], v[180:183], v[188:191], v[104:107]
	v_mfma_f32_16x16x32_bf16 v[100:103], v[172:175], v[196:199], v[100:103]
	v_mfma_f32_16x16x32_bf16 v[92:95], v[180:183], v[196:199], v[92:95]
	v_mfma_f32_16x16x32_bf16 v[84:87], v[172:175], v[204:207], v[84:87]
	v_mfma_f32_16x16x32_bf16 v[76:79], v[180:183], v[204:207], v[76:79]
	v_mfma_f32_16x16x32_bf16 v[68:71], v[172:175], v[212:215], v[68:71]
	v_mfma_f32_16x16x32_bf16 v[64:67], v[180:183], v[212:215], v[64:67]
	s_setprio 0
	s_barrier
	s_add_i32 s18, s49, s26
	v_lshl_add_u64 v[164:165], v[164:165], 0, s[12:13]
	s_mov_b32 m0, s18
	ds_read_b128 v[184:187], v171 offset:49152
	ds_read_b128 v[188:191], v171 offset:50176
	ds_read_b128 v[192:195], v171 offset:51200
	ds_read_b128 v[196:199], v171 offset:52224
	ds_read_b128 v[200:203], v171 offset:53248
	ds_read_b128 v[204:207], v171 offset:54272
	ds_read_b128 v[208:211], v171 offset:55296
	ds_read_b128 v[212:215], v171 offset:56320
	global_load_lds_dwordx4 v[164:165], off
	s_add_i32 m0, s18, 0x2000
	s_add_u32 s18, s22, 0xb0080
	v_lshl_add_u64 v[164:165], v[216:217], 0, s[12:13]
	s_addc_u32 s19, s23, 0
	s_add_i32 s22, s50, s26
	global_load_lds_dwordx4 v[164:165], off
	v_lshl_add_u64 v[164:165], s[18:19], 0, v[132:133]
	s_mov_b32 m0, s22
	s_nop 0
	global_load_lds_dwordx4 v[164:165], off
	v_lshl_add_u64 v[164:165], s[18:19], 0, v[128:129]
	s_add_i32 m0, s22, 0x2000
	s_nop 0
	global_load_lds_dwordx4 v[164:165], off
	v_lshl_add_u64 v[164:165], v[218:219], 0, s[12:13]
	s_mov_b32 m0, s37
	s_nop 0
	global_load_lds_dwordx4 v[164:165], off
	v_lshl_add_u64 v[164:165], v[220:221], 0, s[12:13]
	s_mov_b32 m0, s38
	s_nop 0
	global_load_lds_dwordx4 v[164:165], off
	s_waitcnt vmcnt(8)
	s_waitcnt lgkmcnt(0)
	s_barrier
	s_setprio 0
	s_waitcnt lgkmcnt(0)
	v_mfma_f32_16x16x32_bf16 v[60:63], v[144:147], v[184:187], v[60:63]
	v_mfma_f32_16x16x32_bf16 v[56:59], v[152:155], v[184:187], v[56:59]
	v_mfma_f32_16x16x32_bf16 v[48:51], v[144:147], v[192:195], v[48:51]
	v_mfma_f32_16x16x32_bf16 v[40:43], v[152:155], v[192:195], v[40:43]
	v_mfma_f32_16x16x32_bf16 v[32:35], v[144:147], v[200:203], v[32:35]
	v_mfma_f32_16x16x32_bf16 v[24:27], v[152:155], v[200:203], v[24:27]
	v_mfma_f32_16x16x32_bf16 v[16:19], v[144:147], v[208:211], v[16:19]
	v_mfma_f32_16x16x32_bf16 v[8:11], v[152:155], v[208:211], v[8:11]
	v_mfma_f32_16x16x32_bf16 v[60:63], v[148:151], v[188:191], v[60:63]
	v_mfma_f32_16x16x32_bf16 v[56:59], v[156:159], v[188:191], v[56:59]
	v_mfma_f32_16x16x32_bf16 v[48:51], v[148:151], v[196:199], v[48:51]
	v_mfma_f32_16x16x32_bf16 v[40:43], v[156:159], v[196:199], v[40:43]
	v_mfma_f32_16x16x32_bf16 v[32:35], v[148:151], v[204:207], v[32:35]
	v_mfma_f32_16x16x32_bf16 v[24:27], v[156:159], v[204:207], v[24:27]
	v_mfma_f32_16x16x32_bf16 v[16:19], v[148:151], v[212:215], v[16:19]
	v_mfma_f32_16x16x32_bf16 v[8:11], v[156:159], v[212:215], v[8:11]
	s_setprio 0
	s_setprio 0
	v_mfma_f32_16x16x32_bf16 v[52:55], v[160:163], v[184:187], v[52:55]
	v_mfma_f32_16x16x32_bf16 v[44:47], v[176:179], v[184:187], v[44:47]
	v_mfma_f32_16x16x32_bf16 v[36:39], v[160:163], v[192:195], v[36:39]
	v_mfma_f32_16x16x32_bf16 v[28:31], v[176:179], v[192:195], v[28:31]
	v_mfma_f32_16x16x32_bf16 v[20:23], v[160:163], v[200:203], v[20:23]
	v_mfma_f32_16x16x32_bf16 v[12:15], v[176:179], v[200:203], v[12:15]
	v_mfma_f32_16x16x32_bf16 v[4:7], v[160:163], v[208:211], v[4:7]
	v_mfma_f32_16x16x32_bf16 v[0:3], v[176:179], v[208:211], v[0:3]
	v_mfma_f32_16x16x32_bf16 v[52:55], v[172:175], v[188:191], v[52:55]
	v_mfma_f32_16x16x32_bf16 v[44:47], v[180:183], v[188:191], v[44:47]
	v_mfma_f32_16x16x32_bf16 v[36:39], v[172:175], v[196:199], v[36:39]
	v_mfma_f32_16x16x32_bf16 v[28:31], v[180:183], v[196:199], v[28:31]
	v_mfma_f32_16x16x32_bf16 v[20:23], v[172:175], v[204:207], v[20:23]
	v_mfma_f32_16x16x32_bf16 v[12:15], v[180:183], v[204:207], v[12:15]
	v_mfma_f32_16x16x32_bf16 v[4:7], v[172:175], v[212:215], v[4:7]
	v_mfma_f32_16x16x32_bf16 v[0:3], v[180:183], v[212:215], v[0:3]
	s_setprio 0
	s_barrier
	s_add_i32 s48, s48, 2
	s_add_u32 s46, s46, 0x100
	s_addc_u32 s47, s47, 0
	s_cmp_gt_u32 s48, 41
	s_mov_b64 s[18:19], s[20:21]

.LBB0_430:
	s_add_u32 s28, s28, 0x40080
	s_addc_u32 s29, s29, 0
	s_add_u32 s56, s30, 0x100
	s_addc_u32 s57, s31, 0
	s_mov_b32 s58, -2
	ds_read_b128 v[130:133], v239
	ds_read_b128 v[134:137], v239 offset:1024
	ds_read_b128 v[138:141], v239 offset:2048
	ds_read_b128 v[142:145], v239 offset:3072
	ds_read_b128 v[146:149], v240
	ds_read_b128 v[150:153], v240 offset:1024
	ds_read_b128 v[154:157], v240 offset:2048
	ds_read_b128 v[158:161], v240 offset:3072
	s_add_u32 s30, s28, 0xfffc0080
	s_addc_u32 s31, s29, -1
	s_cmp_eq_u32 s58, 12
	s_cselect_b32 s35, s9, s31
	s_cselect_b32 s34, s23, s30
	s_cselect_b32 s31, s21, s57
	s_cselect_b32 s30, s55, s56
	v_lshl_add_u64 v[80:81], s[28:29], 0, v[222:223]
	s_add_i32 m0, s36, 0xc000
	ds_read_b128 v[162:165], v241
	ds_read_b128 v[166:169], v241 offset:1024
	ds_read_b128 v[170:173], v241 offset:2048
	ds_read_b128 v[174:177], v241 offset:3072
	ds_read_b128 v[178:181], v241 offset:4096
	ds_read_b128 v[182:185], v241 offset:5120
	ds_read_b128 v[186:189], v241 offset:6144
	ds_read_b128 v[190:193], v241 offset:7168
	global_load_lds_dwordx4 v[80:81], off
	v_lshl_add_u64 v[80:81], s[28:29], 0, v[224:225]
	s_add_i32 m0, s36, 0xe000
	s_nop 0
	global_load_lds_dwordx4 v[80:81], off
	s_waitcnt vmcnt(8)
	s_waitcnt lgkmcnt(0)
	s_barrier
	s_setprio 0
	s_waitcnt lgkmcnt(0)
	v_mfma_f32_16x16x32_bf16 v[126:129], v[130:133], v[162:165], 0
	s_add_i32 s54, s54, 1
	s_mul_i32 s6, s54, s44
	s_mul_hi_u32 s7, s54, s49
	v_mfma_f32_16x16x32_bf16 v[122:125], v[138:141], v[162:165], 0
	s_add_i32 s7, s7, s6
	s_mul_i32 s6, s54, s49
	s_add_u32 s24, s6, s96
	v_mfma_f32_16x16x32_bf16 v[110:113], v[130:133], v[170:173], 0
	s_addc_u32 s25, s7, s45
	v_cmp_lt_i64_e64 s[6:7], s[24:25], v[226:227]
	s_ashr_i32 s9, s24, 31
	v_mfma_f32_16x16x32_bf16 v[106:109], v[138:141], v[170:173], 0
	s_lshr_b32 s9, s9, 29
	s_add_i32 s9, s24, s9
	s_ashr_i32 s20, s9, 3
	v_mfma_f32_16x16x32_bf16 v[94:97], v[130:133], v[178:181], 0
	s_and_b32 s9, s9, -8
	s_sub_i32 s9, s24, s9
	s_cmp_lt_i32 s9, 0
	v_mfma_f32_16x16x32_bf16 v[90:93], v[138:141], v[178:181], 0
	s_movk_i32 s21, 0xe1
	s_cselect_b32 s21, s21, 0xe0
	s_mul_i32 s9, s9, s21
	v_mfma_f32_16x16x32_bf16 v[76:79], v[130:133], v[186:189], 0
	s_add_i32 s9, s9, s20
	s_mul_hi_i32 s20, s9, 0x92492493
	s_add_i32 s20, s20, s9
	v_mfma_f32_16x16x32_bf16 v[72:75], v[138:141], v[186:189], 0
	s_lshr_b32 s21, s20, 31
	s_ashr_i32 s20, s20, 6
	s_add_i32 s20, s20, s21
	v_mfma_f32_16x16x32_bf16 v[126:129], v[134:137], v[166:169], v[126:129]
	s_lshl_b32 s21, s20, 3
	s_sub_i32 s22, 0x80, s21
	s_min_i32 s22, s22, 8
	v_mfma_f32_16x16x32_bf16 v[122:125], v[142:145], v[166:169], v[122:125]
	s_abs_i32 s23, s22
	v_cvt_f32_u32_e32 v252, s23
	s_sub_i32 s25, 0, s23
	v_mfma_f32_16x16x32_bf16 v[110:113], v[134:137], v[174:177], v[110:113]
	s_mulk_i32 s20, 0x70
	s_sub_i32 s9, s9, s20
	v_rcp_iflag_f32_e32 v252, v252
	v_mfma_f32_16x16x32_bf16 v[106:109], v[142:145], v[174:177], v[106:109]
	s_abs_i32 s20, s9
	s_xor_b32 s24, s9, s22
	s_ashr_i32 s24, s24, 31
	v_mfma_f32_16x16x32_bf16 v[94:97], v[134:137], v[182:185], v[94:97]
	v_mul_f32_e32 v252, 0x4f7ffffe, v252
	v_cvt_u32_f32_e32 v252, v252
	s_nop 0
	v_mfma_f32_16x16x32_bf16 v[90:93], v[142:145], v[182:185], v[90:93]
	v_readfirstlane_b32 s26, v252
	s_mul_i32 s25, s25, s26
	s_mul_hi_u32 s25, s26, s25
	v_mfma_f32_16x16x32_bf16 v[76:79], v[134:137], v[190:193], v[76:79]
	s_add_i32 s26, s26, s25
	s_mul_hi_u32 s25, s20, s26
	s_mul_i32 s26, s25, s23
	v_mfma_f32_16x16x32_bf16 v[72:75], v[142:145], v[190:193], v[72:75]
	s_sub_i32 s20, s20, s26
	s_add_i32 s27, s25, 1
	s_sub_i32 s26, s20, s23
	s_setprio 0
	s_setprio 0
	v_mfma_f32_16x16x32_bf16 v[118:121], v[146:149], v[162:165], 0
	s_cmp_ge_u32 s20, s23
	s_cselect_b32 s25, s27, s25
	s_cselect_b32 s20, s26, s20
	v_mfma_f32_16x16x32_bf16 v[114:117], v[154:157], v[162:165], 0
	s_add_i32 s26, s25, 1
	s_cmp_ge_u32 s20, s23
	s_cselect_b32 s20, s26, s25
	v_mfma_f32_16x16x32_bf16 v[102:105], v[146:149], v[170:173], 0
	s_xor_b32 s20, s20, s24
	s_sub_i32 s20, s20, s24
	s_mul_i32 s22, s20, s22
	v_mfma_f32_16x16x32_bf16 v[98:101], v[154:157], v[170:173], 0
	s_sub_i32 s9, s9, s22
	s_add_i32 s22, s21, s9
	s_ashr_i32 s23, s22, 31
	v_mfma_f32_16x16x32_bf16 v[86:89], v[146:149], v[178:181], 0
	s_lshl_b64 s[24:25], s[22:23], 19
	s_add_u32 s24, s90, s24
	s_addc_u32 s25, s91, s25
	v_mfma_f32_16x16x32_bf16 v[80:83], v[154:157], v[178:181], 0
	s_and_b64 s[26:27], s[6:7], exec
	s_cselect_b32 s9, s25, s29
	s_cselect_b32 s23, s24, s28
	v_mfma_f32_16x16x32_bf16 v[68:71], v[146:149], v[186:189], 0
	s_ashr_i32 s21, s20, 31
	s_lshl_b64 s[26:27], s[20:21], 19
	s_add_u32 s26, s2, s26
	v_mfma_f32_16x16x32_bf16 v[64:67], v[154:157], v[186:189], 0
	s_addc_u32 s27, s3, s27
	s_and_b64 s[98:99], s[6:7], exec
	s_cselect_b32 s21, s27, s31
	v_mfma_f32_16x16x32_bf16 v[118:121], v[150:153], v[166:169], v[118:121]
	s_cselect_b32 s55, s26, s30
	v_mfma_f32_16x16x32_bf16 v[114:117], v[158:161], v[166:169], v[114:117]
	v_mfma_f32_16x16x32_bf16 v[102:105], v[150:153], v[174:177], v[102:105]
	v_mfma_f32_16x16x32_bf16 v[98:101], v[158:161], v[174:177], v[98:101]
	v_mfma_f32_16x16x32_bf16 v[86:89], v[150:153], v[182:185], v[86:89]
	v_mfma_f32_16x16x32_bf16 v[80:83], v[158:161], v[182:185], v[80:83]
	v_mfma_f32_16x16x32_bf16 v[68:71], v[150:153], v[190:193], v[68:71]
	v_mfma_f32_16x16x32_bf16 v[64:67], v[158:161], v[190:193], v[64:67]
	s_setprio 0
	s_barrier
	s_add_i32 s59, s50, s33
	v_lshl_add_u64 v[194:195], s[30:31], 0, v[212:213]
	s_mov_b32 m0, s59
	ds_read_b128 v[162:165], v241 offset:16384
	ds_read_b128 v[166:169], v241 offset:17408
	ds_read_b128 v[170:173], v241 offset:18432
	ds_read_b128 v[174:177], v241 offset:19456
	ds_read_b128 v[178:181], v241 offset:20480
	ds_read_b128 v[182:185], v241 offset:21504
	ds_read_b128 v[186:189], v241 offset:22528
	ds_read_b128 v[190:193], v241 offset:23552
	global_load_lds_dwordx4 v[194:195], off
	s_add_i32 m0, s59, 0x2000
	s_add_u32 s60, s30, 0x40000
	v_lshl_add_u64 v[196:197], s[30:31], 0, v[216:217]
	s_addc_u32 s61, s31, 0
	s_add_i32 s59, s51, s33
	global_load_lds_dwordx4 v[196:197], off
	v_lshl_add_u64 v[84:85], s[60:61], 0, v[212:213]
	s_mov_b32 m0, s59
	v_lshl_add_u64 v[198:199], s[34:35], 0, v[210:211]
	global_load_lds_dwordx4 v[84:85], off
	v_lshl_add_u64 v[84:85], s[60:61], 0, v[216:217]
	s_add_i32 m0, s59, 0x2000
	v_lshl_add_u64 v[200:201], s[34:35], 0, v[214:215]
	global_load_lds_dwordx4 v[84:85], off
	s_mov_b32 m0, s36
	s_nop 0
	global_load_lds_dwordx4 v[198:199], off
	s_mov_b32 m0, s37
	s_nop 0
	global_load_lds_dwordx4 v[200:201], off
	s_waitcnt vmcnt(8)
	s_waitcnt lgkmcnt(0)
	s_barrier
	s_setprio 0
	s_waitcnt lgkmcnt(0)
	v_mfma_f32_16x16x32_bf16 v[60:63], v[130:133], v[162:165], 0
	v_mfma_f32_16x16x32_bf16 v[56:59], v[138:141], v[162:165], 0
	v_mfma_f32_16x16x32_bf16 v[44:47], v[130:133], v[170:173], 0
	v_mfma_f32_16x16x32_bf16 v[40:43], v[138:141], v[170:173], 0
	v_mfma_f32_16x16x32_bf16 v[28:31], v[130:133], v[178:181], 0
	v_mfma_f32_16x16x32_bf16 v[24:27], v[138:141], v[178:181], 0
	v_mfma_f32_16x16x32_bf16 v[12:15], v[130:133], v[186:189], 0
	v_mfma_f32_16x16x32_bf16 v[8:11], v[138:141], v[186:189], 0
	v_mfma_f32_16x16x32_bf16 v[60:63], v[134:137], v[166:169], v[60:63]
	v_mfma_f32_16x16x32_bf16 v[56:59], v[142:145], v[166:169], v[56:59]
	v_mfma_f32_16x16x32_bf16 v[44:47], v[134:137], v[174:177], v[44:47]
	v_mfma_f32_16x16x32_bf16 v[40:43], v[142:145], v[174:177], v[40:43]
	v_mfma_f32_16x16x32_bf16 v[28:31], v[134:137], v[182:185], v[28:31]
	v_mfma_f32_16x16x32_bf16 v[24:27], v[142:145], v[182:185], v[24:27]
	v_mfma_f32_16x16x32_bf16 v[12:15], v[134:137], v[190:193], v[12:15]
	v_mfma_f32_16x16x32_bf16 v[8:11], v[142:145], v[190:193], v[8:11]
	s_setprio 0
	s_setprio 0
	v_mfma_f32_16x16x32_bf16 v[52:55], v[146:149], v[162:165], 0
	v_mfma_f32_16x16x32_bf16 v[48:51], v[154:157], v[162:165], 0
	v_mfma_f32_16x16x32_bf16 v[36:39], v[146:149], v[170:173], 0
	v_mfma_f32_16x16x32_bf16 v[32:35], v[154:157], v[170:173], 0
	v_mfma_f32_16x16x32_bf16 v[20:23], v[146:149], v[178:181], 0
	v_mfma_f32_16x16x32_bf16 v[16:19], v[154:157], v[178:181], 0
	v_mfma_f32_16x16x32_bf16 v[4:7], v[146:149], v[186:189], 0
	v_mfma_f32_16x16x32_bf16 v[0:3], v[154:157], v[186:189], 0
	v_mfma_f32_16x16x32_bf16 v[52:55], v[150:153], v[166:169], v[52:55]
	v_mfma_f32_16x16x32_bf16 v[48:51], v[158:161], v[166:169], v[48:51]
	v_mfma_f32_16x16x32_bf16 v[36:39], v[150:153], v[174:177], v[36:39]
	v_mfma_f32_16x16x32_bf16 v[32:35], v[158:161], v[174:177], v[32:35]
	v_mfma_f32_16x16x32_bf16 v[20:23], v[150:153], v[182:185], v[20:23]
	v_mfma_f32_16x16x32_bf16 v[16:19], v[158:161], v[182:185], v[16:19]
	v_mfma_f32_16x16x32_bf16 v[4:7], v[150:153], v[190:193], v[4:7]
	v_mfma_f32_16x16x32_bf16 v[0:3], v[158:161], v[190:193], v[0:3]
	s_setprio 0
	s_barrier
	s_add_i32 s59, 0, 0x18000
	v_add_u32_e32 v84, s59, v237
	s_add_i32 s60, 0, 0x1c000
	ds_read_b128 v[130:133], v84
	ds_read_b128 v[134:137], v84 offset:1024
	ds_read_b128 v[138:141], v84 offset:2048
	ds_read_b128 v[142:145], v84 offset:3072
	v_add_u32_e32 v84, s60, v237
	ds_read_b128 v[146:149], v84
	ds_read_b128 v[150:153], v84 offset:1024
	ds_read_b128 v[154:157], v84 offset:2048
	ds_read_b128 v[158:161], v84 offset:3072
	s_add_u32 s34, s34, 0x40000
	s_addc_u32 s35, s35, 0
	s_mov_b32 m0, s38
	v_lshl_add_u64 v[84:85], s[34:35], 0, v[210:211]
	ds_read_b128 v[162:165], v241 offset:32768
	ds_read_b128 v[166:169], v241 offset:33792
	ds_read_b128 v[170:173], v241 offset:34816
	ds_read_b128 v[174:177], v241 offset:35840
	ds_read_b128 v[178:181], v241 offset:36864
	ds_read_b128 v[182:185], v241 offset:37888
	ds_read_b128 v[186:189], v241 offset:38912
	ds_read_b128 v[190:193], v241 offset:39936
	global_load_lds_dwordx4 v[84:85], off
	v_lshl_add_u64 v[84:85], s[34:35], 0, v[214:215]
	s_mov_b32 m0, s39
	s_nop 0
	global_load_lds_dwordx4 v[84:85], off
	s_waitcnt vmcnt(8)
	s_waitcnt lgkmcnt(0)
	s_barrier
	s_setprio 0
	s_waitcnt lgkmcnt(0)
	v_mfma_f32_16x16x32_bf16 v[126:129], v[130:133], v[162:165], v[126:129]
	v_mfma_f32_16x16x32_bf16 v[122:125], v[138:141], v[162:165], v[122:125]
	v_mfma_f32_16x16x32_bf16 v[110:113], v[130:133], v[170:173], v[110:113]
	v_mfma_f32_16x16x32_bf16 v[106:109], v[138:141], v[170:173], v[106:109]
	v_mfma_f32_16x16x32_bf16 v[94:97], v[130:133], v[178:181], v[94:97]
	v_mfma_f32_16x16x32_bf16 v[90:93], v[138:141], v[178:181], v[90:93]
	v_mfma_f32_16x16x32_bf16 v[76:79], v[130:133], v[186:189], v[76:79]
	v_mfma_f32_16x16x32_bf16 v[72:75], v[138:141], v[186:189], v[72:75]
	v_mfma_f32_16x16x32_bf16 v[126:129], v[134:137], v[166:169], v[126:129]
	v_mfma_f32_16x16x32_bf16 v[122:125], v[142:145], v[166:169], v[122:125]
	v_mfma_f32_16x16x32_bf16 v[110:113], v[134:137], v[174:177], v[110:113]
	v_mfma_f32_16x16x32_bf16 v[106:109], v[142:145], v[174:177], v[106:109]
	v_mfma_f32_16x16x32_bf16 v[94:97], v[134:137], v[182:185], v[94:97]
	v_mfma_f32_16x16x32_bf16 v[90:93], v[142:145], v[182:185], v[90:93]
	v_mfma_f32_16x16x32_bf16 v[76:79], v[134:137], v[190:193], v[76:79]
	v_mfma_f32_16x16x32_bf16 v[72:75], v[142:145], v[190:193], v[72:75]
	s_setprio 0
	s_setprio 0
	v_mfma_f32_16x16x32_bf16 v[118:121], v[146:149], v[162:165], v[118:121]
	v_mfma_f32_16x16x32_bf16 v[114:117], v[154:157], v[162:165], v[114:117]
	v_mfma_f32_16x16x32_bf16 v[102:105], v[146:149], v[170:173], v[102:105]
	v_mfma_f32_16x16x32_bf16 v[98:101], v[154:157], v[170:173], v[98:101]
	v_mfma_f32_16x16x32_bf16 v[84:87], v[146:149], v[178:181], v[86:89]
	v_mfma_f32_16x16x32_bf16 v[80:83], v[154:157], v[178:181], v[80:83]
	v_mfma_f32_16x16x32_bf16 v[68:71], v[146:149], v[186:189], v[68:71]
	v_mfma_f32_16x16x32_bf16 v[64:67], v[154:157], v[186:189], v[64:67]
	v_mfma_f32_16x16x32_bf16 v[118:121], v[150:153], v[166:169], v[118:121]
	v_mfma_f32_16x16x32_bf16 v[114:117], v[158:161], v[166:169], v[114:117]
	v_mfma_f32_16x16x32_bf16 v[102:105], v[150:153], v[174:177], v[102:105]
	v_mfma_f32_16x16x32_bf16 v[98:101], v[158:161], v[174:177], v[98:101]
	v_mfma_f32_16x16x32_bf16 v[86:89], v[150:153], v[182:185], v[84:87]
	v_mfma_f32_16x16x32_bf16 v[82:85], v[158:161], v[182:185], v[80:83]
	v_mfma_f32_16x16x32_bf16 v[68:71], v[150:153], v[190:193], v[68:71]
	v_mfma_f32_16x16x32_bf16 v[64:67], v[158:161], v[190:193], v[64:67]
	s_setprio 0
	s_barrier
	s_add_i32 s34, s59, s33
	v_lshl_add_u64 v[80:81], v[194:195], 0, s[16:17]
	s_mov_b32 m0, s34
	ds_read_b128 v[162:165], v241 offset:49152
	ds_read_b128 v[166:169], v241 offset:50176
	ds_read_b128 v[170:173], v241 offset:51200
	ds_read_b128 v[174:177], v241 offset:52224
	ds_read_b128 v[178:181], v241 offset:53248
	ds_read_b128 v[182:185], v241 offset:54272
	ds_read_b128 v[186:189], v241 offset:55296
	ds_read_b128 v[190:193], v241 offset:56320
	global_load_lds_dwordx4 v[80:81], off
	s_add_i32 m0, s34, 0x2000
	s_add_u32 s30, s30, 0x40080
	v_lshl_add_u64 v[80:81], v[196:197], 0, s[16:17]
	s_addc_u32 s31, s31, 0
	s_add_i32 s34, s60, s33
	global_load_lds_dwordx4 v[80:81], off
	v_lshl_add_u64 v[80:81], s[30:31], 0, v[212:213]
	s_mov_b32 m0, s34
	s_nop 0
	global_load_lds_dwordx4 v[80:81], off
	v_lshl_add_u64 v[80:81], s[30:31], 0, v[216:217]
	s_add_i32 m0, s34, 0x2000
	s_nop 0
	global_load_lds_dwordx4 v[80:81], off
	v_lshl_add_u64 v[80:81], v[198:199], 0, s[16:17]
	s_mov_b32 m0, s47
	s_nop 0
	global_load_lds_dwordx4 v[80:81], off
	v_lshl_add_u64 v[80:81], v[200:201], 0, s[16:17]
	s_mov_b32 m0, s48
	s_nop 0
	global_load_lds_dwordx4 v[80:81], off
	s_waitcnt vmcnt(8)
	s_waitcnt lgkmcnt(0)
	s_barrier
	s_setprio 0
	s_waitcnt lgkmcnt(0)
	v_mfma_f32_16x16x32_bf16 v[60:63], v[130:133], v[162:165], v[60:63]
	v_mfma_f32_16x16x32_bf16 v[56:59], v[138:141], v[162:165], v[56:59]
	v_mfma_f32_16x16x32_bf16 v[44:47], v[130:133], v[170:173], v[44:47]
	v_mfma_f32_16x16x32_bf16 v[40:43], v[138:141], v[170:173], v[40:43]
	v_mfma_f32_16x16x32_bf16 v[28:31], v[130:133], v[178:181], v[28:31]
	v_mfma_f32_16x16x32_bf16 v[24:27], v[138:141], v[178:181], v[24:27]
	v_mfma_f32_16x16x32_bf16 v[12:15], v[130:133], v[186:189], v[12:15]
	v_mfma_f32_16x16x32_bf16 v[8:11], v[138:141], v[186:189], v[8:11]
	v_mfma_f32_16x16x32_bf16 v[60:63], v[134:137], v[166:169], v[60:63]
	v_mfma_f32_16x16x32_bf16 v[56:59], v[142:145], v[166:169], v[56:59]
	v_mfma_f32_16x16x32_bf16 v[44:47], v[134:137], v[174:177], v[44:47]
	v_mfma_f32_16x16x32_bf16 v[40:43], v[142:145], v[174:177], v[40:43]
	v_mfma_f32_16x16x32_bf16 v[28:31], v[134:137], v[182:185], v[28:31]
	v_mfma_f32_16x16x32_bf16 v[24:27], v[142:145], v[182:185], v[24:27]
	v_mfma_f32_16x16x32_bf16 v[12:15], v[134:137], v[190:193], v[12:15]
	v_mfma_f32_16x16x32_bf16 v[8:11], v[142:145], v[190:193], v[8:11]
	s_setprio 0
	s_setprio 0
	v_mfma_f32_16x16x32_bf16 v[52:55], v[146:149], v[162:165], v[52:55]
	v_mfma_f32_16x16x32_bf16 v[48:51], v[154:157], v[162:165], v[48:51]
	v_mfma_f32_16x16x32_bf16 v[36:39], v[146:149], v[170:173], v[36:39]
	v_mfma_f32_16x16x32_bf16 v[32:35], v[154:157], v[170:173], v[32:35]
	v_mfma_f32_16x16x32_bf16 v[20:23], v[146:149], v[178:181], v[20:23]
	v_mfma_f32_16x16x32_bf16 v[16:19], v[154:157], v[178:181], v[16:19]
	v_mfma_f32_16x16x32_bf16 v[4:7], v[146:149], v[186:189], v[4:7]
	v_mfma_f32_16x16x32_bf16 v[0:3], v[154:157], v[186:189], v[0:3]
	v_mfma_f32_16x16x32_bf16 v[52:55], v[150:153], v[166:169], v[52:55]
	v_mfma_f32_16x16x32_bf16 v[48:51], v[158:161], v[166:169], v[48:51]
	v_mfma_f32_16x16x32_bf16 v[36:39], v[150:153], v[174:177], v[36:39]
	v_mfma_f32_16x16x32_bf16 v[32:35], v[158:161], v[174:177], v[32:35]
	v_mfma_f32_16x16x32_bf16 v[20:23], v[150:153], v[182:185], v[20:23]
	v_mfma_f32_16x16x32_bf16 v[16:19], v[158:161], v[182:185], v[16:19]
	v_mfma_f32_16x16x32_bf16 v[4:7], v[150:153], v[190:193], v[4:7]
	v_mfma_f32_16x16x32_bf16 v[0:3], v[158:161], v[190:193], v[0:3]
	s_setprio 0
	s_barrier
	s_add_i32 s58, s58, 2
	s_add_u32 s28, s28, 0x100
	s_addc_u32 s29, s29, 0
	s_add_u32 s56, s56, 0x100
	s_addc_u32 s57, s57, 0
	s_cmp_gt_u32 s58, 13

.LBB0_1025:
	s_ashr_i32 s23, s22, 31
	s_lshl_b64 s[24:25], s[22:23], 19
	s_add_u32 s24, s90, s24
	s_addc_u32 s25, s91, s25
	s_and_b64 s[26:27], s[6:7], exec
	s_cselect_b32 s23, s25, s35
	s_cselect_b32 s29, s24, s34
	s_ashr_i32 s21, s20, 31
	s_lshl_b64 s[26:27], s[20:21], 19
	s_add_u32 s26, s2, s26
	s_addc_u32 s27, s3, s27
	s_and_b64 s[38:39], s[6:7], exec
	s_cselect_b32 s21, s27, s37
	s_cselect_b32 s55, s26, s36
	s_add_u32 s34, s34, 0x40080
	s_addc_u32 s35, s35, 0
	s_add_u32 s56, s36, 0x100
	s_addc_u32 s57, s37, 0
	s_mov_b32 s58, -2
	s_waitcnt lgkmcnt(0)
	s_waitcnt vmcnt(0)
	ds_read_b128 v[128:131], v187
	ds_read_b128 v[132:135], v187 offset:1024
	ds_read_b128 v[152:155], v187 offset:2048
	ds_read_b128 v[156:159], v187 offset:3072
	ds_read_b128 v[160:163], v188
	ds_read_b128 v[164:167], v188 offset:1024
	ds_read_b128 v[168:171], v188 offset:2048
	ds_read_b128 v[172:175], v188 offset:3072
	s_add_u32 s36, s34, 0xfffc0080
	s_addc_u32 s37, s35, -1
	s_cmp_eq_u32 s58, 12
	s_cselect_b32 s39, s23, s37
	s_cselect_b32 s38, s29, s36
	s_cselect_b32 s37, s21, s57
	s_cselect_b32 s36, s55, s56
	v_lshl_add_u64 v[216:217], s[34:35], 0, v[144:145]
	s_add_i32 m0, s31, 0xc000
	ds_read_b128 v[176:179], v189
	ds_read_b128 v[180:183], v189 offset:1024
	ds_read_b128 v[192:195], v189 offset:2048
	ds_read_b128 v[196:199], v189 offset:3072
	ds_read_b128 v[200:203], v189 offset:4096
	ds_read_b128 v[204:207], v189 offset:5120
	ds_read_b128 v[208:211], v189 offset:6144
	ds_read_b128 v[212:215], v189 offset:7168
	global_load_lds_dwordx4 v[216:217], off
	v_lshl_add_u64 v[216:217], s[34:35], 0, v[146:147]
	s_add_i32 m0, s31, 0xe000
	s_nop 0
	global_load_lds_dwordx4 v[216:217], off
	s_waitcnt vmcnt(8)
	s_waitcnt lgkmcnt(0)
	s_barrier
	s_setprio 0
	s_waitcnt lgkmcnt(0)
	v_mfma_f32_16x16x32_bf16 v[124:127], v[128:131], v[176:179], 0
	v_mfma_f32_16x16x32_bf16 v[120:123], v[152:155], v[176:179], 0
	v_mfma_f32_16x16x32_bf16 v[108:111], v[128:131], v[192:195], 0
	v_mfma_f32_16x16x32_bf16 v[104:107], v[152:155], v[192:195], 0
	v_mfma_f32_16x16x32_bf16 v[92:95], v[128:131], v[200:203], 0
	v_mfma_f32_16x16x32_bf16 v[88:91], v[152:155], v[200:203], 0
	v_mfma_f32_16x16x32_bf16 v[76:79], v[128:131], v[208:211], 0
	v_mfma_f32_16x16x32_bf16 v[72:75], v[152:155], v[208:211], 0
	v_mfma_f32_16x16x32_bf16 v[124:127], v[132:135], v[180:183], v[124:127]
	v_mfma_f32_16x16x32_bf16 v[120:123], v[156:159], v[180:183], v[120:123]
	v_mfma_f32_16x16x32_bf16 v[108:111], v[132:135], v[196:199], v[108:111]
	v_mfma_f32_16x16x32_bf16 v[104:107], v[156:159], v[196:199], v[104:107]
	v_mfma_f32_16x16x32_bf16 v[92:95], v[132:135], v[204:207], v[92:95]
	v_mfma_f32_16x16x32_bf16 v[88:91], v[156:159], v[204:207], v[88:91]
	v_mfma_f32_16x16x32_bf16 v[76:79], v[132:135], v[212:215], v[76:79]
	v_mfma_f32_16x16x32_bf16 v[72:75], v[156:159], v[212:215], v[72:75]
	s_setprio 0
	s_setprio 0
	v_mfma_f32_16x16x32_bf16 v[116:119], v[160:163], v[176:179], 0
	v_mfma_f32_16x16x32_bf16 v[112:115], v[168:171], v[176:179], 0
	v_mfma_f32_16x16x32_bf16 v[100:103], v[160:163], v[192:195], 0
	v_mfma_f32_16x16x32_bf16 v[96:99], v[168:171], v[192:195], 0
	v_mfma_f32_16x16x32_bf16 v[84:87], v[160:163], v[200:203], 0
	v_mfma_f32_16x16x32_bf16 v[80:83], v[168:171], v[200:203], 0
	v_mfma_f32_16x16x32_bf16 v[68:71], v[160:163], v[208:211], 0
	v_mfma_f32_16x16x32_bf16 v[64:67], v[168:171], v[208:211], 0
	v_mfma_f32_16x16x32_bf16 v[116:119], v[164:167], v[180:183], v[116:119]
	v_mfma_f32_16x16x32_bf16 v[112:115], v[172:175], v[180:183], v[112:115]
	v_mfma_f32_16x16x32_bf16 v[100:103], v[164:167], v[196:199], v[100:103]
	v_mfma_f32_16x16x32_bf16 v[96:99], v[172:175], v[196:199], v[96:99]
	v_mfma_f32_16x16x32_bf16 v[84:87], v[164:167], v[204:207], v[84:87]
	v_mfma_f32_16x16x32_bf16 v[80:83], v[172:175], v[204:207], v[80:83]
	v_mfma_f32_16x16x32_bf16 v[68:71], v[164:167], v[212:215], v[68:71]
	v_mfma_f32_16x16x32_bf16 v[64:67], v[172:175], v[212:215], v[64:67]
	s_setprio 0
	s_barrier
	s_add_i32 s59, s53, s33
	v_lshl_add_u64 v[216:217], s[36:37], 0, v[138:139]
	s_mov_b32 m0, s59
	ds_read_b128 v[176:179], v189 offset:16384
	ds_read_b128 v[180:183], v189 offset:17408
	ds_read_b128 v[192:195], v189 offset:18432
	ds_read_b128 v[196:199], v189 offset:19456
	ds_read_b128 v[200:203], v189 offset:20480
	ds_read_b128 v[204:207], v189 offset:21504
	ds_read_b128 v[208:211], v189 offset:22528
	ds_read_b128 v[212:215], v189 offset:23552
	global_load_lds_dwordx4 v[216:217], off
	s_add_i32 m0, s59, 0x2000
	s_add_u32 s60, s36, 0x40000
	v_lshl_add_u64 v[218:219], s[36:37], 0, v[142:143]
	s_addc_u32 s61, s37, 0
	s_add_i32 s59, s54, s33
	global_load_lds_dwordx4 v[218:219], off
	v_lshl_add_u64 v[220:221], s[60:61], 0, v[138:139]
	s_mov_b32 m0, s59
	v_lshl_add_u64 v[222:223], s[38:39], 0, v[140:141]
	global_load_lds_dwordx4 v[220:221], off
	v_lshl_add_u64 v[220:221], s[60:61], 0, v[142:143]
	s_add_i32 m0, s59, 0x2000
	s_nop 0
	global_load_lds_dwordx4 v[220:221], off
	v_lshl_add_u64 v[220:221], s[38:39], 0, v[136:137]
	s_mov_b32 m0, s31
	s_nop 0
	global_load_lds_dwordx4 v[220:221], off
	s_mov_b32 m0, s40
	s_nop 0
	global_load_lds_dwordx4 v[222:223], off
	s_waitcnt vmcnt(8)
	s_waitcnt lgkmcnt(0)
	s_barrier
	s_setprio 0
	s_waitcnt lgkmcnt(0)
	v_mfma_f32_16x16x32_bf16 v[60:63], v[128:131], v[176:179], 0
	v_mfma_f32_16x16x32_bf16 v[56:59], v[152:155], v[176:179], 0
	v_mfma_f32_16x16x32_bf16 v[44:47], v[128:131], v[192:195], 0
	v_mfma_f32_16x16x32_bf16 v[40:43], v[152:155], v[192:195], 0
	v_mfma_f32_16x16x32_bf16 v[28:31], v[128:131], v[200:203], 0
	v_mfma_f32_16x16x32_bf16 v[24:27], v[152:155], v[200:203], 0
	v_mfma_f32_16x16x32_bf16 v[12:15], v[128:131], v[208:211], 0
	v_mfma_f32_16x16x32_bf16 v[8:11], v[152:155], v[208:211], 0
	v_mfma_f32_16x16x32_bf16 v[60:63], v[132:135], v[180:183], v[60:63]
	v_mfma_f32_16x16x32_bf16 v[56:59], v[156:159], v[180:183], v[56:59]
	v_mfma_f32_16x16x32_bf16 v[44:47], v[132:135], v[196:199], v[44:47]
	v_mfma_f32_16x16x32_bf16 v[40:43], v[156:159], v[196:199], v[40:43]
	v_mfma_f32_16x16x32_bf16 v[28:31], v[132:135], v[204:207], v[28:31]
	v_mfma_f32_16x16x32_bf16 v[24:27], v[156:159], v[204:207], v[24:27]
	v_mfma_f32_16x16x32_bf16 v[12:15], v[132:135], v[212:215], v[12:15]
	v_mfma_f32_16x16x32_bf16 v[8:11], v[156:159], v[212:215], v[8:11]
	s_setprio 0
	s_setprio 0
	v_mfma_f32_16x16x32_bf16 v[52:55], v[160:163], v[176:179], 0
	v_mfma_f32_16x16x32_bf16 v[48:51], v[168:171], v[176:179], 0
	v_mfma_f32_16x16x32_bf16 v[36:39], v[160:163], v[192:195], 0
	v_mfma_f32_16x16x32_bf16 v[32:35], v[168:171], v[192:195], 0
	v_mfma_f32_16x16x32_bf16 v[20:23], v[160:163], v[200:203], 0
	v_mfma_f32_16x16x32_bf16 v[16:19], v[168:171], v[200:203], 0
	v_mfma_f32_16x16x32_bf16 v[4:7], v[160:163], v[208:211], 0
	v_mfma_f32_16x16x32_bf16 v[0:3], v[168:171], v[208:211], 0
	v_mfma_f32_16x16x32_bf16 v[52:55], v[164:167], v[180:183], v[52:55]
	v_mfma_f32_16x16x32_bf16 v[48:51], v[172:175], v[180:183], v[48:51]
	v_mfma_f32_16x16x32_bf16 v[36:39], v[164:167], v[196:199], v[36:39]
	v_mfma_f32_16x16x32_bf16 v[32:35], v[172:175], v[196:199], v[32:35]
	v_mfma_f32_16x16x32_bf16 v[20:23], v[164:167], v[204:207], v[20:23]
	v_mfma_f32_16x16x32_bf16 v[16:19], v[172:175], v[204:207], v[16:19]
	v_mfma_f32_16x16x32_bf16 v[4:7], v[164:167], v[212:215], v[4:7]
	v_mfma_f32_16x16x32_bf16 v[0:3], v[172:175], v[212:215], v[0:3]
	s_setprio 0
	s_barrier
	s_add_i32 s59, 0, 0x18000
	s_add_i32 s60, 0, 0x1c000
	v_add_u32_e32 v156, s59, v185
	v_add_u32_e32 v172, s60, v185
	ds_read_b128 v[128:131], v156
	ds_read_b128 v[132:135], v156 offset:1024
	ds_read_b128 v[152:155], v156 offset:2048
	ds_read_b128 v[156:159], v156 offset:3072
	ds_read_b128 v[160:163], v172
	ds_read_b128 v[164:167], v172 offset:1024
	ds_read_b128 v[168:171], v172 offset:2048
	ds_read_b128 v[172:175], v172 offset:3072
	s_add_u32 s38, s38, 0x40000
	s_addc_u32 s39, s39, 0
	s_mov_b32 m0, s41
	v_lshl_add_u64 v[224:225], s[38:39], 0, v[136:137]
	ds_read_b128 v[176:179], v189 offset:32768
	ds_read_b128 v[180:183], v189 offset:33792
	ds_read_b128 v[192:195], v189 offset:34816
	ds_read_b128 v[196:199], v189 offset:35840
	ds_read_b128 v[200:203], v189 offset:36864
	ds_read_b128 v[204:207], v189 offset:37888
	ds_read_b128 v[208:211], v189 offset:38912
	ds_read_b128 v[212:215], v189 offset:39936
	global_load_lds_dwordx4 v[224:225], off
	v_lshl_add_u64 v[224:225], s[38:39], 0, v[140:141]
	s_mov_b32 m0, s42
	s_nop 0
	global_load_lds_dwordx4 v[224:225], off
	s_waitcnt vmcnt(8)
	s_waitcnt lgkmcnt(0)
	s_barrier
	s_setprio 0
	s_waitcnt lgkmcnt(0)
	v_mfma_f32_16x16x32_bf16 v[124:127], v[128:131], v[176:179], v[124:127]
	v_mfma_f32_16x16x32_bf16 v[120:123], v[152:155], v[176:179], v[120:123]
	v_mfma_f32_16x16x32_bf16 v[108:111], v[128:131], v[192:195], v[108:111]
	v_mfma_f32_16x16x32_bf16 v[104:107], v[152:155], v[192:195], v[104:107]
	v_mfma_f32_16x16x32_bf16 v[92:95], v[128:131], v[200:203], v[92:95]
	v_mfma_f32_16x16x32_bf16 v[88:91], v[152:155], v[200:203], v[88:91]
	v_mfma_f32_16x16x32_bf16 v[76:79], v[128:131], v[208:211], v[76:79]
	v_mfma_f32_16x16x32_bf16 v[72:75], v[152:155], v[208:211], v[72:75]
	v_mfma_f32_16x16x32_bf16 v[124:127], v[132:135], v[180:183], v[124:127]
	v_mfma_f32_16x16x32_bf16 v[120:123], v[156:159], v[180:183], v[120:123]
	v_mfma_f32_16x16x32_bf16 v[108:111], v[132:135], v[196:199], v[108:111]
	v_mfma_f32_16x16x32_bf16 v[104:107], v[156:159], v[196:199], v[104:107]
	v_mfma_f32_16x16x32_bf16 v[92:95], v[132:135], v[204:207], v[92:95]
	v_mfma_f32_16x16x32_bf16 v[88:91], v[156:159], v[204:207], v[88:91]
	v_mfma_f32_16x16x32_bf16 v[76:79], v[132:135], v[212:215], v[76:79]
	v_mfma_f32_16x16x32_bf16 v[72:75], v[156:159], v[212:215], v[72:75]
	s_setprio 0
	s_setprio 0
	v_mfma_f32_16x16x32_bf16 v[116:119], v[160:163], v[176:179], v[116:119]
	v_mfma_f32_16x16x32_bf16 v[112:115], v[168:171], v[176:179], v[112:115]
	v_mfma_f32_16x16x32_bf16 v[100:103], v[160:163], v[192:195], v[100:103]
	v_mfma_f32_16x16x32_bf16 v[96:99], v[168:171], v[192:195], v[96:99]
	v_mfma_f32_16x16x32_bf16 v[84:87], v[160:163], v[200:203], v[84:87]
	v_mfma_f32_16x16x32_bf16 v[80:83], v[168:171], v[200:203], v[80:83]
	v_mfma_f32_16x16x32_bf16 v[68:71], v[160:163], v[208:211], v[68:71]
	v_mfma_f32_16x16x32_bf16 v[64:67], v[168:171], v[208:211], v[64:67]
	v_mfma_f32_16x16x32_bf16 v[116:119], v[164:167], v[180:183], v[116:119]
	v_mfma_f32_16x16x32_bf16 v[112:115], v[172:175], v[180:183], v[112:115]
	v_mfma_f32_16x16x32_bf16 v[100:103], v[164:167], v[196:199], v[100:103]
	v_mfma_f32_16x16x32_bf16 v[96:99], v[172:175], v[196:199], v[96:99]
	v_mfma_f32_16x16x32_bf16 v[84:87], v[164:167], v[204:207], v[84:87]
	v_mfma_f32_16x16x32_bf16 v[80:83], v[172:175], v[204:207], v[80:83]
	v_mfma_f32_16x16x32_bf16 v[68:71], v[164:167], v[212:215], v[68:71]
	v_mfma_f32_16x16x32_bf16 v[64:67], v[172:175], v[212:215], v[64:67]
	s_setprio 0
	s_barrier
	s_add_i32 s38, s59, s33
	v_lshl_add_u64 v[216:217], v[216:217], 0, s[16:17]
	s_mov_b32 m0, s38
	ds_read_b128 v[176:179], v189 offset:49152
	ds_read_b128 v[180:183], v189 offset:50176
	ds_read_b128 v[192:195], v189 offset:51200
	ds_read_b128 v[196:199], v189 offset:52224
	ds_read_b128 v[200:203], v189 offset:53248
	ds_read_b128 v[204:207], v189 offset:54272
	ds_read_b128 v[208:211], v189 offset:55296
	ds_read_b128 v[212:215], v189 offset:56320
	global_load_lds_dwordx4 v[216:217], off
	s_add_i32 m0, s38, 0x2000
	s_add_u32 s36, s36, 0x40080
	v_lshl_add_u64 v[216:217], v[218:219], 0, s[16:17]
	s_addc_u32 s37, s37, 0
	s_add_i32 s38, s60, s33
	global_load_lds_dwordx4 v[216:217], off
	v_lshl_add_u64 v[216:217], s[36:37], 0, v[138:139]
	s_mov_b32 m0, s38
	s_nop 0
	global_load_lds_dwordx4 v[216:217], off
	v_lshl_add_u64 v[216:217], s[36:37], 0, v[142:143]
	s_add_i32 m0, s38, 0x2000
	s_nop 0
	global_load_lds_dwordx4 v[216:217], off
	v_lshl_add_u64 v[216:217], v[220:221], 0, s[16:17]
	s_mov_b32 m0, s48
	s_nop 0
	global_load_lds_dwordx4 v[216:217], off
	v_lshl_add_u64 v[216:217], v[222:223], 0, s[16:17]
	s_mov_b32 m0, s49
	s_nop 0
	global_load_lds_dwordx4 v[216:217], off
	s_waitcnt vmcnt(8)
	s_waitcnt lgkmcnt(0)
	s_barrier
	s_setprio 0
	s_waitcnt lgkmcnt(0)
	v_mfma_f32_16x16x32_bf16 v[60:63], v[128:131], v[176:179], v[60:63]
	v_mfma_f32_16x16x32_bf16 v[56:59], v[152:155], v[176:179], v[56:59]
	v_mfma_f32_16x16x32_bf16 v[44:47], v[128:131], v[192:195], v[44:47]
	v_mfma_f32_16x16x32_bf16 v[40:43], v[152:155], v[192:195], v[40:43]
	v_mfma_f32_16x16x32_bf16 v[28:31], v[128:131], v[200:203], v[28:31]
	v_mfma_f32_16x16x32_bf16 v[24:27], v[152:155], v[200:203], v[24:27]
	v_mfma_f32_16x16x32_bf16 v[12:15], v[128:131], v[208:211], v[12:15]
	v_mfma_f32_16x16x32_bf16 v[8:11], v[152:155], v[208:211], v[8:11]
	v_mfma_f32_16x16x32_bf16 v[60:63], v[132:135], v[180:183], v[60:63]
	v_mfma_f32_16x16x32_bf16 v[56:59], v[156:159], v[180:183], v[56:59]
	v_mfma_f32_16x16x32_bf16 v[44:47], v[132:135], v[196:199], v[44:47]
	v_mfma_f32_16x16x32_bf16 v[40:43], v[156:159], v[196:199], v[40:43]
	v_mfma_f32_16x16x32_bf16 v[28:31], v[132:135], v[204:207], v[28:31]
	v_mfma_f32_16x16x32_bf16 v[24:27], v[156:159], v[204:207], v[24:27]
	v_mfma_f32_16x16x32_bf16 v[12:15], v[132:135], v[212:215], v[12:15]
	v_mfma_f32_16x16x32_bf16 v[8:11], v[156:159], v[212:215], v[8:11]
	s_setprio 0
	s_setprio 0
	v_mfma_f32_16x16x32_bf16 v[52:55], v[160:163], v[176:179], v[52:55]
	v_mfma_f32_16x16x32_bf16 v[48:51], v[168:171], v[176:179], v[48:51]
	v_mfma_f32_16x16x32_bf16 v[36:39], v[160:163], v[192:195], v[36:39]
	v_mfma_f32_16x16x32_bf16 v[32:35], v[168:171], v[192:195], v[32:35]
	v_mfma_f32_16x16x32_bf16 v[20:23], v[160:163], v[200:203], v[20:23]
	v_mfma_f32_16x16x32_bf16 v[16:19], v[168:171], v[200:203], v[16:19]
	v_mfma_f32_16x16x32_bf16 v[4:7], v[160:163], v[208:211], v[4:7]
	v_mfma_f32_16x16x32_bf16 v[0:3], v[168:171], v[208:211], v[0:3]
	v_mfma_f32_16x16x32_bf16 v[52:55], v[164:167], v[180:183], v[52:55]
	v_mfma_f32_16x16x32_bf16 v[48:51], v[172:175], v[180:183], v[48:51]
	v_mfma_f32_16x16x32_bf16 v[36:39], v[164:167], v[196:199], v[36:39]
	v_mfma_f32_16x16x32_bf16 v[32:35], v[172:175], v[196:199], v[32:35]
	v_mfma_f32_16x16x32_bf16 v[20:23], v[164:167], v[204:207], v[20:23]
	v_mfma_f32_16x16x32_bf16 v[16:19], v[172:175], v[204:207], v[16:19]
	v_mfma_f32_16x16x32_bf16 v[4:7], v[164:167], v[212:215], v[4:7]
	v_mfma_f32_16x16x32_bf16 v[0:3], v[172:175], v[212:215], v[0:3]
	s_setprio 0
	s_barrier
	s_add_i32 s58, s58, 2
	s_add_u32 s34, s34, 0x100
	s_addc_u32 s35, s35, 0
	s_add_u32 s56, s56, 0x100
	s_addc_u32 s57, s57, 0
	s_cmp_gt_u32 s58, 13

.LBB0_1110:
	s_add_u32 s24, s24, 0x40080
	s_addc_u32 s25, s25, 0
	s_add_u32 s53, s26, 0x100
	s_addc_u32 s54, s27, 0
	s_mov_b32 s55, -2
	s_waitcnt vmcnt(0)
	ds_read_b128 v[124:127], v171
	ds_read_b128 v[132:135], v171 offset:1024
	ds_read_b128 v[136:139], v171 offset:2048
	ds_read_b128 v[140:143], v171 offset:3072
	ds_read_b128 v[162:165], v175
	ds_read_b128 v[182:185], v175 offset:1024
	ds_read_b128 v[186:189], v175 offset:2048
	ds_read_b128 v[190:193], v175 offset:3072
	s_add_u32 s26, s24, 0xfffc0080
	s_addc_u32 s27, s25, -1
	s_cmp_eq_u32 s55, 12
	s_cselect_b32 s29, s17, s27
	s_cselect_b32 s28, s51, s26
	s_cselect_b32 s27, s15, s54
	s_cselect_b32 s26, s52, s53
	v_lshl_add_u64 v[172:173], s[24:25], 0, v[152:153]
	s_add_i32 m0, s23, 0xc000
	ds_read_b128 v[194:197], v179
	ds_read_b128 v[198:201], v179 offset:1024
	ds_read_b128 v[202:205], v179 offset:2048
	ds_read_b128 v[206:209], v179 offset:3072
	ds_read_b128 v[210:213], v179 offset:4096
	ds_read_b128 v[214:217], v179 offset:5120
	ds_read_b128 v[218:221], v179 offset:6144
	ds_read_b128 v[222:225], v179 offset:7168
	global_load_lds_dwordx4 v[172:173], off
	v_lshl_add_u64 v[172:173], s[24:25], 0, v[154:155]
	s_add_i32 m0, s23, 0xe000
	s_nop 0
	global_load_lds_dwordx4 v[172:173], off
	s_waitcnt vmcnt(8)
	s_waitcnt lgkmcnt(0)
	s_barrier
	s_setprio 0
	s_waitcnt lgkmcnt(0)
	v_mfma_f32_16x16x32_bf16 v[128:131], v[124:127], v[194:197], 0
	s_add_i32 s39, s39, 1
	s_mul_i32 s0, s39, s42
	s_mul_hi_u32 s1, s39, s45
	v_mfma_f32_16x16x32_bf16 v[120:123], v[136:139], v[194:197], 0
	s_add_i32 s1, s1, s0
	s_mul_i32 s0, s39, s45
	s_add_u32 s18, s0, s96
	v_mfma_f32_16x16x32_bf16 v[108:111], v[124:127], v[202:205], 0
	s_addc_u32 s19, s1, s34
	v_cmp_lt_i64_e64 s[0:1], s[18:19], v[156:157]
	s_ashr_i32 s14, s18, 31
	v_mfma_f32_16x16x32_bf16 v[104:107], v[136:139], v[202:205], 0
	s_lshr_b32 s14, s14, 29
	s_add_i32 s14, s18, s14
	s_ashr_i32 s15, s14, 3
	v_mfma_f32_16x16x32_bf16 v[92:95], v[124:127], v[210:213], 0
	s_and_b32 s14, s14, -8
	s_sub_i32 s14, s18, s14
	s_cmp_lt_i32 s14, 0
	v_mfma_f32_16x16x32_bf16 v[88:91], v[136:139], v[210:213], 0
	s_cselect_b32 s16, s35, 0x160
	s_mul_i32 s14, s14, s16
	s_add_i32 s14, s14, s15
	v_mfma_f32_16x16x32_bf16 v[76:79], v[124:127], v[218:221], 0
	s_mul_hi_i32 s15, s14, 0x2e8ba2e9
	s_lshr_b32 s16, s15, 31
	s_ashr_i32 s15, s15, 5
	v_mfma_f32_16x16x32_bf16 v[72:75], v[136:139], v[218:221], 0
	s_add_i32 s15, s15, s16
	s_lshl_b32 s16, s15, 3
	s_sub_i32 s17, 0x80, s16
	v_mfma_f32_16x16x32_bf16 v[128:131], v[132:135], v[198:201], v[128:131]
	s_min_i32 s17, s17, 8
	s_abs_i32 s18, s17
	v_cvt_f32_u32_e32 v252, s18
	v_mfma_f32_16x16x32_bf16 v[120:123], v[140:143], v[198:201], v[120:123]
	s_sub_i32 s20, 0, s18
	s_mulk_i32 s15, 0xb0
	s_sub_i32 s15, s14, s15
	v_mfma_f32_16x16x32_bf16 v[108:111], v[132:135], v[206:209], v[108:111]
	v_rcp_iflag_f32_e32 v252, v252
	s_abs_i32 s14, s15
	s_xor_b32 s19, s15, s17
	v_mfma_f32_16x16x32_bf16 v[104:107], v[140:143], v[206:209], v[104:107]
	s_ashr_i32 s19, s19, 31
	v_mul_f32_e32 v252, 0x4f7ffffe, v252
	v_cvt_u32_f32_e32 v252, v252
	v_mfma_f32_16x16x32_bf16 v[92:95], v[132:135], v[214:217], v[92:95]
	s_nop 0
	v_readfirstlane_b32 s21, v252
	s_mul_i32 s20, s20, s21
	v_mfma_f32_16x16x32_bf16 v[88:91], v[140:143], v[214:217], v[88:91]
	s_mul_hi_u32 s20, s21, s20
	s_add_i32 s21, s21, s20
	s_mul_hi_u32 s20, s14, s21
	v_mfma_f32_16x16x32_bf16 v[76:79], v[132:135], v[222:225], v[76:79]
	s_mul_i32 s21, s20, s18
	s_sub_i32 s14, s14, s21
	s_add_i32 s98, s20, 1
	v_mfma_f32_16x16x32_bf16 v[72:75], v[140:143], v[222:225], v[72:75]
	s_sub_i32 s21, s14, s18
	s_cmp_ge_u32 s14, s18
	s_cselect_b32 s20, s98, s20
	s_setprio 0
	s_setprio 0
	v_mfma_f32_16x16x32_bf16 v[116:119], v[162:165], v[194:197], 0
	s_cselect_b32 s14, s21, s14
	s_add_i32 s21, s20, 1
	s_cmp_ge_u32 s14, s18
	v_mfma_f32_16x16x32_bf16 v[112:115], v[186:189], v[194:197], 0
	s_cselect_b32 s14, s21, s20
	s_xor_b32 s14, s14, s19
	s_sub_i32 s14, s14, s19
	v_mfma_f32_16x16x32_bf16 v[100:103], v[162:165], v[202:205], 0
	s_mul_i32 s17, s14, s17
	s_sub_i32 s15, s15, s17
	s_add_i32 s16, s16, s15
	v_mfma_f32_16x16x32_bf16 v[96:99], v[186:189], v[202:205], 0
	s_ashr_i32 s17, s16, 31
	s_lshl_b64 s[18:19], s[16:17], 19
	s_add_u32 s18, s2, s18
	v_mfma_f32_16x16x32_bf16 v[84:87], v[162:165], v[210:213], 0
	s_addc_u32 s19, s3, s19
	s_and_b64 s[20:21], s[0:1], exec
	s_cselect_b32 s17, s19, s25
	v_mfma_f32_16x16x32_bf16 v[80:83], v[186:189], v[210:213], 0
	s_cselect_b32 s51, s18, s24
	s_ashr_i32 s15, s14, 31
	s_lshl_b64 s[20:21], s[14:15], 19
	v_mfma_f32_16x16x32_bf16 v[68:71], v[162:165], v[218:221], 0
	s_add_u32 s20, s30, s20
	s_addc_u32 s21, s31, s21
	s_and_b64 s[98:99], s[0:1], exec
	v_mfma_f32_16x16x32_bf16 v[64:67], v[186:189], v[218:221], 0
	s_cselect_b32 s15, s21, s27
	s_cselect_b32 s52, s20, s26
	v_mfma_f32_16x16x32_bf16 v[116:119], v[182:185], v[198:201], v[116:119]
	v_mfma_f32_16x16x32_bf16 v[112:115], v[190:193], v[198:201], v[112:115]
	v_mfma_f32_16x16x32_bf16 v[100:103], v[182:185], v[206:209], v[100:103]
	v_mfma_f32_16x16x32_bf16 v[96:99], v[190:193], v[206:209], v[96:99]
	v_mfma_f32_16x16x32_bf16 v[84:87], v[182:185], v[214:217], v[84:87]
	v_mfma_f32_16x16x32_bf16 v[80:83], v[190:193], v[214:217], v[80:83]
	v_mfma_f32_16x16x32_bf16 v[68:71], v[182:185], v[222:225], v[68:71]
	v_mfma_f32_16x16x32_bf16 v[64:67], v[190:193], v[222:225], v[64:67]
	s_setprio 0
	s_barrier
	s_add_i32 s56, s46, s33
	v_lshl_add_u64 v[172:173], s[26:27], 0, v[148:149]
	s_mov_b32 m0, s56
	ds_read_b128 v[194:197], v179 offset:16384
	ds_read_b128 v[198:201], v179 offset:17408
	ds_read_b128 v[202:205], v179 offset:18432
	ds_read_b128 v[206:209], v179 offset:19456
	ds_read_b128 v[210:213], v179 offset:20480
	ds_read_b128 v[214:217], v179 offset:21504
	ds_read_b128 v[218:221], v179 offset:22528
	ds_read_b128 v[222:225], v179 offset:23552
	global_load_lds_dwordx4 v[172:173], off
	s_add_i32 m0, s56, 0x2000
	s_add_u32 s56, s26, 0x40000
	v_lshl_add_u64 v[176:177], s[26:27], 0, v[144:145]
	s_addc_u32 s57, s27, 0
	s_add_i32 s58, s47, s33
	global_load_lds_dwordx4 v[176:177], off
	v_lshl_add_u64 v[226:227], s[56:57], 0, v[148:149]
	s_mov_b32 m0, s58
	v_lshl_add_u64 v[228:229], s[28:29], 0, v[146:147]
	global_load_lds_dwordx4 v[226:227], off
	v_lshl_add_u64 v[226:227], s[56:57], 0, v[144:145]
	s_add_i32 m0, s58, 0x2000
	s_nop 0
	global_load_lds_dwordx4 v[226:227], off
	v_lshl_add_u64 v[226:227], s[28:29], 0, v[150:151]
	s_mov_b32 m0, s23
	s_nop 0
	global_load_lds_dwordx4 v[226:227], off
	s_mov_b32 m0, s36
	s_nop 0
	global_load_lds_dwordx4 v[228:229], off
	s_waitcnt vmcnt(8)
	s_waitcnt lgkmcnt(0)
	s_barrier
	s_setprio 0
	s_waitcnt lgkmcnt(0)
	v_mfma_f32_16x16x32_bf16 v[60:63], v[124:127], v[194:197], 0
	v_mfma_f32_16x16x32_bf16 v[56:59], v[136:139], v[194:197], 0
	v_mfma_f32_16x16x32_bf16 v[44:47], v[124:127], v[202:205], 0
	v_mfma_f32_16x16x32_bf16 v[40:43], v[136:139], v[202:205], 0
	v_mfma_f32_16x16x32_bf16 v[28:31], v[124:127], v[210:213], 0
	v_mfma_f32_16x16x32_bf16 v[24:27], v[136:139], v[210:213], 0
	v_mfma_f32_16x16x32_bf16 v[12:15], v[124:127], v[218:221], 0
	v_mfma_f32_16x16x32_bf16 v[8:11], v[136:139], v[218:221], 0
	v_mfma_f32_16x16x32_bf16 v[60:63], v[132:135], v[198:201], v[60:63]
	v_mfma_f32_16x16x32_bf16 v[56:59], v[140:143], v[198:201], v[56:59]
	v_mfma_f32_16x16x32_bf16 v[44:47], v[132:135], v[206:209], v[44:47]
	v_mfma_f32_16x16x32_bf16 v[40:43], v[140:143], v[206:209], v[40:43]
	v_mfma_f32_16x16x32_bf16 v[28:31], v[132:135], v[214:217], v[28:31]
	v_mfma_f32_16x16x32_bf16 v[24:27], v[140:143], v[214:217], v[24:27]
	v_mfma_f32_16x16x32_bf16 v[12:15], v[132:135], v[222:225], v[12:15]
	v_mfma_f32_16x16x32_bf16 v[8:11], v[140:143], v[222:225], v[8:11]
	s_setprio 0
	s_setprio 0
	v_mfma_f32_16x16x32_bf16 v[52:55], v[162:165], v[194:197], 0
	v_mfma_f32_16x16x32_bf16 v[48:51], v[186:189], v[194:197], 0
	v_mfma_f32_16x16x32_bf16 v[36:39], v[162:165], v[202:205], 0
	v_mfma_f32_16x16x32_bf16 v[32:35], v[186:189], v[202:205], 0
	v_mfma_f32_16x16x32_bf16 v[20:23], v[162:165], v[210:213], 0
	v_mfma_f32_16x16x32_bf16 v[16:19], v[186:189], v[210:213], 0
	v_mfma_f32_16x16x32_bf16 v[4:7], v[162:165], v[218:221], 0
	v_mfma_f32_16x16x32_bf16 v[0:3], v[186:189], v[218:221], 0
	v_mfma_f32_16x16x32_bf16 v[52:55], v[182:185], v[198:201], v[52:55]
	v_mfma_f32_16x16x32_bf16 v[48:51], v[190:193], v[198:201], v[48:51]
	v_mfma_f32_16x16x32_bf16 v[36:39], v[182:185], v[206:209], v[36:39]
	v_mfma_f32_16x16x32_bf16 v[32:35], v[190:193], v[206:209], v[32:35]
	v_mfma_f32_16x16x32_bf16 v[20:23], v[182:185], v[214:217], v[20:23]
	v_mfma_f32_16x16x32_bf16 v[16:19], v[190:193], v[214:217], v[16:19]
	v_mfma_f32_16x16x32_bf16 v[4:7], v[182:185], v[222:225], v[4:7]
	v_mfma_f32_16x16x32_bf16 v[0:3], v[190:193], v[222:225], v[0:3]
	s_setprio 0
	s_barrier
	s_add_i32 s56, 0, 0x18000
	s_add_i32 s57, 0, 0x1c000
	v_add_u32_e32 v140, s56, v167
	v_add_u32_e32 v160, s57, v167
	ds_read_b128 v[124:127], v140
	ds_read_b128 v[132:135], v140 offset:1024
	ds_read_b128 v[136:139], v140 offset:2048
	ds_read_b128 v[140:143], v140 offset:3072
	ds_read_b128 v[162:165], v160
	ds_read_b128 v[182:185], v160 offset:1024
	ds_read_b128 v[186:189], v160 offset:2048
	ds_read_b128 v[190:193], v160 offset:3072
	s_add_u32 s28, s28, 0x40000
	s_addc_u32 s29, s29, 0
	s_mov_b32 m0, s37
	v_lshl_add_u64 v[230:231], s[28:29], 0, v[150:151]
	ds_read_b128 v[194:197], v179 offset:32768
	ds_read_b128 v[198:201], v179 offset:33792
	ds_read_b128 v[202:205], v179 offset:34816
	ds_read_b128 v[206:209], v179 offset:35840
	ds_read_b128 v[210:213], v179 offset:36864
	ds_read_b128 v[214:217], v179 offset:37888
	ds_read_b128 v[218:221], v179 offset:38912
	ds_read_b128 v[222:225], v179 offset:39936
	global_load_lds_dwordx4 v[230:231], off
	v_lshl_add_u64 v[230:231], s[28:29], 0, v[146:147]
	s_mov_b32 m0, s38
	s_nop 0
	global_load_lds_dwordx4 v[230:231], off
	s_waitcnt vmcnt(8)
	s_waitcnt lgkmcnt(0)
	s_barrier
	s_setprio 0
	s_waitcnt lgkmcnt(0)
	v_mfma_f32_16x16x32_bf16 v[128:131], v[124:127], v[194:197], v[128:131]
	v_mfma_f32_16x16x32_bf16 v[120:123], v[136:139], v[194:197], v[120:123]
	v_mfma_f32_16x16x32_bf16 v[108:111], v[124:127], v[202:205], v[108:111]
	v_mfma_f32_16x16x32_bf16 v[104:107], v[136:139], v[202:205], v[104:107]
	v_mfma_f32_16x16x32_bf16 v[92:95], v[124:127], v[210:213], v[92:95]
	v_mfma_f32_16x16x32_bf16 v[88:91], v[136:139], v[210:213], v[88:91]
	v_mfma_f32_16x16x32_bf16 v[76:79], v[124:127], v[218:221], v[76:79]
	v_mfma_f32_16x16x32_bf16 v[72:75], v[136:139], v[218:221], v[72:75]
	v_mfma_f32_16x16x32_bf16 v[128:131], v[132:135], v[198:201], v[128:131]
	v_mfma_f32_16x16x32_bf16 v[120:123], v[140:143], v[198:201], v[120:123]
	v_mfma_f32_16x16x32_bf16 v[108:111], v[132:135], v[206:209], v[108:111]
	v_mfma_f32_16x16x32_bf16 v[104:107], v[140:143], v[206:209], v[104:107]
	v_mfma_f32_16x16x32_bf16 v[92:95], v[132:135], v[214:217], v[92:95]
	v_mfma_f32_16x16x32_bf16 v[88:91], v[140:143], v[214:217], v[88:91]
	v_mfma_f32_16x16x32_bf16 v[76:79], v[132:135], v[222:225], v[76:79]
	v_mfma_f32_16x16x32_bf16 v[72:75], v[140:143], v[222:225], v[72:75]
	s_setprio 0
	s_setprio 0
	v_mfma_f32_16x16x32_bf16 v[116:119], v[162:165], v[194:197], v[116:119]
	v_mfma_f32_16x16x32_bf16 v[112:115], v[186:189], v[194:197], v[112:115]
	v_mfma_f32_16x16x32_bf16 v[100:103], v[162:165], v[202:205], v[100:103]
	v_mfma_f32_16x16x32_bf16 v[96:99], v[186:189], v[202:205], v[96:99]
	v_mfma_f32_16x16x32_bf16 v[84:87], v[162:165], v[210:213], v[84:87]
	v_mfma_f32_16x16x32_bf16 v[80:83], v[186:189], v[210:213], v[80:83]
	v_mfma_f32_16x16x32_bf16 v[68:71], v[162:165], v[218:221], v[68:71]
	v_mfma_f32_16x16x32_bf16 v[64:67], v[186:189], v[218:221], v[64:67]
	v_mfma_f32_16x16x32_bf16 v[116:119], v[182:185], v[198:201], v[116:119]
	v_mfma_f32_16x16x32_bf16 v[112:115], v[190:193], v[198:201], v[112:115]
	v_mfma_f32_16x16x32_bf16 v[100:103], v[182:185], v[206:209], v[100:103]
	v_mfma_f32_16x16x32_bf16 v[96:99], v[190:193], v[206:209], v[96:99]
	v_mfma_f32_16x16x32_bf16 v[84:87], v[182:185], v[214:217], v[84:87]
	v_mfma_f32_16x16x32_bf16 v[80:83], v[190:193], v[214:217], v[80:83]
	v_mfma_f32_16x16x32_bf16 v[68:71], v[182:185], v[222:225], v[68:71]
	v_mfma_f32_16x16x32_bf16 v[64:67], v[190:193], v[222:225], v[64:67]
	s_setprio 0
	s_barrier
	s_add_i32 s28, s56, s33
	v_lshl_add_u64 v[172:173], v[172:173], 0, s[10:11]
	s_mov_b32 m0, s28
	ds_read_b128 v[194:197], v179 offset:49152
	ds_read_b128 v[198:201], v179 offset:50176
	ds_read_b128 v[202:205], v179 offset:51200
	ds_read_b128 v[206:209], v179 offset:52224
	ds_read_b128 v[210:213], v179 offset:53248
	ds_read_b128 v[214:217], v179 offset:54272
	ds_read_b128 v[218:221], v179 offset:55296
	ds_read_b128 v[222:225], v179 offset:56320
	global_load_lds_dwordx4 v[172:173], off
	s_add_i32 m0, s28, 0x2000
	s_add_u32 s26, s26, 0x40080
	v_lshl_add_u64 v[172:173], v[176:177], 0, s[10:11]
	s_addc_u32 s27, s27, 0
	s_add_i32 s28, s57, s33
	global_load_lds_dwordx4 v[172:173], off
	v_lshl_add_u64 v[172:173], s[26:27], 0, v[148:149]
	s_mov_b32 m0, s28
	s_nop 0
	global_load_lds_dwordx4 v[172:173], off
	v_lshl_add_u64 v[172:173], s[26:27], 0, v[144:145]
	s_add_i32 m0, s28, 0x2000
	s_nop 0
	global_load_lds_dwordx4 v[172:173], off
	v_lshl_add_u64 v[172:173], v[226:227], 0, s[10:11]
	s_mov_b32 m0, s43
	s_nop 0
	global_load_lds_dwordx4 v[172:173], off
	v_lshl_add_u64 v[172:173], v[228:229], 0, s[10:11]
	s_mov_b32 m0, s44
	s_nop 0
	global_load_lds_dwordx4 v[172:173], off
	s_waitcnt vmcnt(8)
	s_waitcnt lgkmcnt(0)
	s_barrier
	s_setprio 0
	s_waitcnt lgkmcnt(0)
	v_mfma_f32_16x16x32_bf16 v[60:63], v[124:127], v[194:197], v[60:63]
	v_mfma_f32_16x16x32_bf16 v[56:59], v[136:139], v[194:197], v[56:59]
	v_mfma_f32_16x16x32_bf16 v[44:47], v[124:127], v[202:205], v[44:47]
	v_mfma_f32_16x16x32_bf16 v[40:43], v[136:139], v[202:205], v[40:43]
	v_mfma_f32_16x16x32_bf16 v[28:31], v[124:127], v[210:213], v[28:31]
	v_mfma_f32_16x16x32_bf16 v[24:27], v[136:139], v[210:213], v[24:27]
	v_mfma_f32_16x16x32_bf16 v[12:15], v[124:127], v[218:221], v[12:15]
	v_mfma_f32_16x16x32_bf16 v[8:11], v[136:139], v[218:221], v[8:11]
	v_mfma_f32_16x16x32_bf16 v[60:63], v[132:135], v[198:201], v[60:63]
	v_mfma_f32_16x16x32_bf16 v[56:59], v[140:143], v[198:201], v[56:59]
	v_mfma_f32_16x16x32_bf16 v[44:47], v[132:135], v[206:209], v[44:47]
	v_mfma_f32_16x16x32_bf16 v[40:43], v[140:143], v[206:209], v[40:43]
	v_mfma_f32_16x16x32_bf16 v[28:31], v[132:135], v[214:217], v[28:31]
	v_mfma_f32_16x16x32_bf16 v[24:27], v[140:143], v[214:217], v[24:27]
	v_mfma_f32_16x16x32_bf16 v[12:15], v[132:135], v[222:225], v[12:15]
	v_mfma_f32_16x16x32_bf16 v[8:11], v[140:143], v[222:225], v[8:11]
	s_setprio 0
	s_setprio 0
	v_mfma_f32_16x16x32_bf16 v[52:55], v[162:165], v[194:197], v[52:55]
	v_mfma_f32_16x16x32_bf16 v[48:51], v[186:189], v[194:197], v[48:51]
	v_mfma_f32_16x16x32_bf16 v[36:39], v[162:165], v[202:205], v[36:39]
	v_mfma_f32_16x16x32_bf16 v[32:35], v[186:189], v[202:205], v[32:35]
	v_mfma_f32_16x16x32_bf16 v[20:23], v[162:165], v[210:213], v[20:23]
	v_mfma_f32_16x16x32_bf16 v[16:19], v[186:189], v[210:213], v[16:19]
	v_mfma_f32_16x16x32_bf16 v[4:7], v[162:165], v[218:221], v[4:7]
	v_mfma_f32_16x16x32_bf16 v[0:3], v[186:189], v[218:221], v[0:3]
	v_mfma_f32_16x16x32_bf16 v[52:55], v[182:185], v[198:201], v[52:55]
	v_mfma_f32_16x16x32_bf16 v[48:51], v[190:193], v[198:201], v[48:51]
	v_mfma_f32_16x16x32_bf16 v[36:39], v[182:185], v[206:209], v[36:39]
	v_mfma_f32_16x16x32_bf16 v[32:35], v[190:193], v[206:209], v[32:35]
	v_mfma_f32_16x16x32_bf16 v[20:23], v[182:185], v[214:217], v[20:23]
	v_mfma_f32_16x16x32_bf16 v[16:19], v[190:193], v[214:217], v[16:19]
	v_mfma_f32_16x16x32_bf16 v[4:7], v[182:185], v[222:225], v[4:7]
	v_mfma_f32_16x16x32_bf16 v[0:3], v[190:193], v[222:225], v[0:3]
	s_setprio 0
	s_barrier
	s_add_i32 s55, s55, 2
	s_add_u32 s24, s24, 0x100
	s_addc_u32 s25, s25, 0
	s_add_u32 s53, s53, 0x100
	s_addc_u32 s54, s54, 0
	s_cmp_gt_u32 s55, 13

.LBB0_1195:
	s_add_u32 s41, s16, 0x100
	s_addc_u32 s42, s17, 0
	s_mov_b32 s43, -2
	s_waitcnt vmcnt(0)
	ds_read_b128 v[144:147], v171
	ds_read_b128 v[148:151], v171 offset:1024
	ds_read_b128 v[152:155], v171 offset:2048
	ds_read_b128 v[156:159], v171 offset:3072
	ds_read_b128 v[160:163], v172
	ds_read_b128 v[164:167], v172 offset:1024
	ds_read_b128 v[174:177], v172 offset:2048
	ds_read_b128 v[178:181], v172 offset:3072
	s_add_u32 s16, s14, 0x100
	s_addc_u32 s17, s15, 0
	s_cmp_eq_u32 s43, 40
	s_cselect_b32 s21, s5, s17
	s_cselect_b32 s20, s4, s16
	s_cselect_b32 s19, s13, s42
	s_cselect_b32 s18, s12, s41
	v_lshl_add_u64 v[214:215], s[14:15], 0, v[136:137]
	s_add_i32 m0, s24, 0xc000
	ds_read_b128 v[182:185], v173
	ds_read_b128 v[186:189], v173 offset:1024
	ds_read_b128 v[190:193], v173 offset:2048
	ds_read_b128 v[194:197], v173 offset:3072
	ds_read_b128 v[198:201], v173 offset:4096
	ds_read_b128 v[202:205], v173 offset:5120
	ds_read_b128 v[206:209], v173 offset:6144
	ds_read_b128 v[210:213], v173 offset:7168
	global_load_lds_dwordx4 v[214:215], off
	v_lshl_add_u64 v[214:215], s[14:15], 0, v[138:139]
	s_add_i32 m0, s24, 0xe000
	s_nop 0
	global_load_lds_dwordx4 v[214:215], off
	s_waitcnt vmcnt(8)
	s_waitcnt lgkmcnt(0)
	s_barrier
	s_setprio 0
	s_waitcnt lgkmcnt(0)
	v_mfma_f32_16x16x32_bf16 v[124:127], v[144:147], v[182:185], 0
	v_mfma_f32_16x16x32_bf16 v[120:123], v[152:155], v[182:185], 0
	v_mfma_f32_16x16x32_bf16 v[112:115], v[144:147], v[190:193], 0
	v_mfma_f32_16x16x32_bf16 v[104:107], v[152:155], v[190:193], 0
	v_mfma_f32_16x16x32_bf16 v[96:99], v[144:147], v[198:201], 0
	v_mfma_f32_16x16x32_bf16 v[88:91], v[152:155], v[198:201], 0
	v_mfma_f32_16x16x32_bf16 v[80:83], v[144:147], v[206:209], 0
	v_mfma_f32_16x16x32_bf16 v[72:75], v[152:155], v[206:209], 0
	v_mfma_f32_16x16x32_bf16 v[124:127], v[148:151], v[186:189], v[124:127]
	v_mfma_f32_16x16x32_bf16 v[120:123], v[156:159], v[186:189], v[120:123]
	v_mfma_f32_16x16x32_bf16 v[112:115], v[148:151], v[194:197], v[112:115]
	v_mfma_f32_16x16x32_bf16 v[104:107], v[156:159], v[194:197], v[104:107]
	v_mfma_f32_16x16x32_bf16 v[96:99], v[148:151], v[202:205], v[96:99]
	v_mfma_f32_16x16x32_bf16 v[88:91], v[156:159], v[202:205], v[88:91]
	v_mfma_f32_16x16x32_bf16 v[80:83], v[148:151], v[210:213], v[80:83]
	v_mfma_f32_16x16x32_bf16 v[72:75], v[156:159], v[210:213], v[72:75]
	s_setprio 0
	s_setprio 0
	v_mfma_f32_16x16x32_bf16 v[116:119], v[160:163], v[182:185], 0
	v_mfma_f32_16x16x32_bf16 v[108:111], v[174:177], v[182:185], 0
	v_mfma_f32_16x16x32_bf16 v[100:103], v[160:163], v[190:193], 0
	v_mfma_f32_16x16x32_bf16 v[92:95], v[174:177], v[190:193], 0
	v_mfma_f32_16x16x32_bf16 v[84:87], v[160:163], v[198:201], 0
	v_mfma_f32_16x16x32_bf16 v[76:79], v[174:177], v[198:201], 0
	v_mfma_f32_16x16x32_bf16 v[68:71], v[160:163], v[206:209], 0
	v_mfma_f32_16x16x32_bf16 v[64:67], v[174:177], v[206:209], 0
	v_mfma_f32_16x16x32_bf16 v[116:119], v[164:167], v[186:189], v[116:119]
	v_mfma_f32_16x16x32_bf16 v[108:111], v[178:181], v[186:189], v[108:111]
	v_mfma_f32_16x16x32_bf16 v[100:103], v[164:167], v[194:197], v[100:103]
	v_mfma_f32_16x16x32_bf16 v[92:95], v[178:181], v[194:197], v[92:95]
	v_mfma_f32_16x16x32_bf16 v[84:87], v[164:167], v[202:205], v[84:87]
	v_mfma_f32_16x16x32_bf16 v[76:79], v[178:181], v[202:205], v[76:79]
	v_mfma_f32_16x16x32_bf16 v[68:71], v[164:167], v[210:213], v[68:71]
	v_mfma_f32_16x16x32_bf16 v[64:67], v[178:181], v[210:213], v[64:67]
	s_setprio 0
	s_barrier
	s_add_i32 s14, s35, s23
	v_lshl_add_u64 v[214:215], s[18:19], 0, v[130:131]
	s_mov_b32 m0, s14
	ds_read_b128 v[182:185], v173 offset:16384
	ds_read_b128 v[186:189], v173 offset:17408
	ds_read_b128 v[190:193], v173 offset:18432
	ds_read_b128 v[194:197], v173 offset:19456
	ds_read_b128 v[198:201], v173 offset:20480
	ds_read_b128 v[202:205], v173 offset:21504
	ds_read_b128 v[206:209], v173 offset:22528
	ds_read_b128 v[210:213], v173 offset:23552
	global_load_lds_dwordx4 v[214:215], off
	s_add_i32 m0, s14, 0x2000
	s_add_u32 s14, s18, 0xb0000
	v_lshl_add_u64 v[216:217], s[18:19], 0, v[134:135]
	s_addc_u32 s15, s19, 0
	s_add_i32 s44, s36, s23
	global_load_lds_dwordx4 v[216:217], off
	v_lshl_add_u64 v[218:219], s[14:15], 0, v[130:131]
	s_mov_b32 m0, s44
	v_lshl_add_u64 v[220:221], s[20:21], 0, v[132:133]
	global_load_lds_dwordx4 v[218:219], off
	v_lshl_add_u64 v[218:219], s[14:15], 0, v[134:135]
	s_add_i32 m0, s44, 0x2000
	s_nop 0
	global_load_lds_dwordx4 v[218:219], off
	v_lshl_add_u64 v[218:219], s[20:21], 0, v[128:129]
	s_mov_b32 m0, s24
	s_nop 0
	global_load_lds_dwordx4 v[218:219], off
	s_mov_b32 m0, s25
	s_nop 0
	global_load_lds_dwordx4 v[220:221], off
	s_waitcnt vmcnt(8)
	s_waitcnt lgkmcnt(0)
	s_barrier
	s_setprio 0
	s_waitcnt lgkmcnt(0)
	v_mfma_f32_16x16x32_bf16 v[60:63], v[144:147], v[182:185], 0
	v_mfma_f32_16x16x32_bf16 v[56:59], v[152:155], v[182:185], 0
	v_mfma_f32_16x16x32_bf16 v[48:51], v[144:147], v[190:193], 0
	v_mfma_f32_16x16x32_bf16 v[40:43], v[152:155], v[190:193], 0
	v_mfma_f32_16x16x32_bf16 v[32:35], v[144:147], v[198:201], 0
	v_mfma_f32_16x16x32_bf16 v[24:27], v[152:155], v[198:201], 0
	v_mfma_f32_16x16x32_bf16 v[16:19], v[144:147], v[206:209], 0
	v_mfma_f32_16x16x32_bf16 v[8:11], v[152:155], v[206:209], 0
	v_mfma_f32_16x16x32_bf16 v[60:63], v[148:151], v[186:189], v[60:63]
	v_mfma_f32_16x16x32_bf16 v[56:59], v[156:159], v[186:189], v[56:59]
	v_mfma_f32_16x16x32_bf16 v[48:51], v[148:151], v[194:197], v[48:51]
	v_mfma_f32_16x16x32_bf16 v[40:43], v[156:159], v[194:197], v[40:43]
	v_mfma_f32_16x16x32_bf16 v[32:35], v[148:151], v[202:205], v[32:35]
	v_mfma_f32_16x16x32_bf16 v[24:27], v[156:159], v[202:205], v[24:27]
	v_mfma_f32_16x16x32_bf16 v[16:19], v[148:151], v[210:213], v[16:19]
	v_mfma_f32_16x16x32_bf16 v[8:11], v[156:159], v[210:213], v[8:11]
	s_setprio 0
	s_setprio 0
	v_mfma_f32_16x16x32_bf16 v[52:55], v[160:163], v[182:185], 0
	v_mfma_f32_16x16x32_bf16 v[44:47], v[174:177], v[182:185], 0
	v_mfma_f32_16x16x32_bf16 v[36:39], v[160:163], v[190:193], 0
	v_mfma_f32_16x16x32_bf16 v[28:31], v[174:177], v[190:193], 0
	v_mfma_f32_16x16x32_bf16 v[20:23], v[160:163], v[198:201], 0
	v_mfma_f32_16x16x32_bf16 v[12:15], v[174:177], v[198:201], 0
	v_mfma_f32_16x16x32_bf16 v[4:7], v[160:163], v[206:209], 0
	v_mfma_f32_16x16x32_bf16 v[0:3], v[174:177], v[206:209], 0
	v_mfma_f32_16x16x32_bf16 v[52:55], v[164:167], v[186:189], v[52:55]
	v_mfma_f32_16x16x32_bf16 v[44:47], v[178:181], v[186:189], v[44:47]
	v_mfma_f32_16x16x32_bf16 v[36:39], v[164:167], v[194:197], v[36:39]
	v_mfma_f32_16x16x32_bf16 v[28:31], v[178:181], v[194:197], v[28:31]
	v_mfma_f32_16x16x32_bf16 v[20:23], v[164:167], v[202:205], v[20:23]
	v_mfma_f32_16x16x32_bf16 v[12:15], v[178:181], v[202:205], v[12:15]
	v_mfma_f32_16x16x32_bf16 v[4:7], v[164:167], v[210:213], v[4:7]
	v_mfma_f32_16x16x32_bf16 v[0:3], v[178:181], v[210:213], v[0:3]
	s_setprio 0
	s_barrier
	s_add_i32 s44, 0, 0x18000
	s_add_i32 s45, 0, 0x1c000
	v_add_u32_e32 v156, s44, v169
	v_add_u32_e32 v178, s45, v169
	ds_read_b128 v[144:147], v156
	ds_read_b128 v[148:151], v156 offset:1024
	ds_read_b128 v[152:155], v156 offset:2048
	ds_read_b128 v[156:159], v156 offset:3072
	ds_read_b128 v[160:163], v178
	ds_read_b128 v[164:167], v178 offset:1024
	ds_read_b128 v[174:177], v178 offset:2048
	ds_read_b128 v[178:181], v178 offset:3072
	s_add_u32 s14, s20, 0xb0000
	s_addc_u32 s15, s21, 0
	s_mov_b32 m0, s26
	v_lshl_add_u64 v[222:223], s[14:15], 0, v[128:129]
	ds_read_b128 v[182:185], v173 offset:32768
	ds_read_b128 v[186:189], v173 offset:33792
	ds_read_b128 v[190:193], v173 offset:34816
	ds_read_b128 v[194:197], v173 offset:35840
	ds_read_b128 v[198:201], v173 offset:36864
	ds_read_b128 v[202:205], v173 offset:37888
	ds_read_b128 v[206:209], v173 offset:38912
	ds_read_b128 v[210:213], v173 offset:39936
	global_load_lds_dwordx4 v[222:223], off
	v_lshl_add_u64 v[222:223], s[14:15], 0, v[132:133]
	s_mov_b32 m0, s27
	s_nop 0
	global_load_lds_dwordx4 v[222:223], off
	s_waitcnt vmcnt(8)
	s_waitcnt lgkmcnt(0)
	s_barrier
	s_setprio 0
	s_waitcnt lgkmcnt(0)
	v_mfma_f32_16x16x32_bf16 v[124:127], v[144:147], v[182:185], v[124:127]
	v_mfma_f32_16x16x32_bf16 v[120:123], v[152:155], v[182:185], v[120:123]
	v_mfma_f32_16x16x32_bf16 v[112:115], v[144:147], v[190:193], v[112:115]
	v_mfma_f32_16x16x32_bf16 v[104:107], v[152:155], v[190:193], v[104:107]
	v_mfma_f32_16x16x32_bf16 v[96:99], v[144:147], v[198:201], v[96:99]
	v_mfma_f32_16x16x32_bf16 v[88:91], v[152:155], v[198:201], v[88:91]
	v_mfma_f32_16x16x32_bf16 v[80:83], v[144:147], v[206:209], v[80:83]
	v_mfma_f32_16x16x32_bf16 v[72:75], v[152:155], v[206:209], v[72:75]
	v_mfma_f32_16x16x32_bf16 v[124:127], v[148:151], v[186:189], v[124:127]
	v_mfma_f32_16x16x32_bf16 v[120:123], v[156:159], v[186:189], v[120:123]
	v_mfma_f32_16x16x32_bf16 v[112:115], v[148:151], v[194:197], v[112:115]
	v_mfma_f32_16x16x32_bf16 v[104:107], v[156:159], v[194:197], v[104:107]
	v_mfma_f32_16x16x32_bf16 v[96:99], v[148:151], v[202:205], v[96:99]
	v_mfma_f32_16x16x32_bf16 v[88:91], v[156:159], v[202:205], v[88:91]
	v_mfma_f32_16x16x32_bf16 v[80:83], v[148:151], v[210:213], v[80:83]
	v_mfma_f32_16x16x32_bf16 v[72:75], v[156:159], v[210:213], v[72:75]
	s_setprio 0
	s_setprio 0
	v_mfma_f32_16x16x32_bf16 v[116:119], v[160:163], v[182:185], v[116:119]
	v_mfma_f32_16x16x32_bf16 v[108:111], v[174:177], v[182:185], v[108:111]
	v_mfma_f32_16x16x32_bf16 v[100:103], v[160:163], v[190:193], v[100:103]
	v_mfma_f32_16x16x32_bf16 v[92:95], v[174:177], v[190:193], v[92:95]
	v_mfma_f32_16x16x32_bf16 v[84:87], v[160:163], v[198:201], v[84:87]
	v_mfma_f32_16x16x32_bf16 v[76:79], v[174:177], v[198:201], v[76:79]
	v_mfma_f32_16x16x32_bf16 v[68:71], v[160:163], v[206:209], v[68:71]
	v_mfma_f32_16x16x32_bf16 v[64:67], v[174:177], v[206:209], v[64:67]
	v_mfma_f32_16x16x32_bf16 v[116:119], v[164:167], v[186:189], v[116:119]
	v_mfma_f32_16x16x32_bf16 v[108:111], v[178:181], v[186:189], v[108:111]
	v_mfma_f32_16x16x32_bf16 v[100:103], v[164:167], v[194:197], v[100:103]
	v_mfma_f32_16x16x32_bf16 v[92:95], v[178:181], v[194:197], v[92:95]
	v_mfma_f32_16x16x32_bf16 v[84:87], v[164:167], v[202:205], v[84:87]
	v_mfma_f32_16x16x32_bf16 v[76:79], v[178:181], v[202:205], v[76:79]
	v_mfma_f32_16x16x32_bf16 v[68:71], v[164:167], v[210:213], v[68:71]
	v_mfma_f32_16x16x32_bf16 v[64:67], v[178:181], v[210:213], v[64:67]
	s_setprio 0
	s_barrier
	s_add_i32 s14, s44, s23
	v_lshl_add_u64 v[214:215], v[214:215], 0, s[8:9]
	s_mov_b32 m0, s14
	ds_read_b128 v[182:185], v173 offset:49152
	ds_read_b128 v[186:189], v173 offset:50176
	ds_read_b128 v[190:193], v173 offset:51200
	ds_read_b128 v[194:197], v173 offset:52224
	ds_read_b128 v[198:201], v173 offset:53248
	ds_read_b128 v[202:205], v173 offset:54272
	ds_read_b128 v[206:209], v173 offset:55296
	ds_read_b128 v[210:213], v173 offset:56320
	global_load_lds_dwordx4 v[214:215], off
	s_add_i32 m0, s14, 0x2000
	s_add_u32 s14, s18, 0xb0080
	v_lshl_add_u64 v[214:215], v[216:217], 0, s[8:9]
	s_addc_u32 s15, s19, 0
	s_add_i32 s18, s45, s23
	global_load_lds_dwordx4 v[214:215], off
	v_lshl_add_u64 v[214:215], s[14:15], 0, v[130:131]
	s_mov_b32 m0, s18
	s_nop 0
	global_load_lds_dwordx4 v[214:215], off
	v_lshl_add_u64 v[214:215], s[14:15], 0, v[134:135]
	s_add_i32 m0, s18, 0x2000
	s_nop 0
	global_load_lds_dwordx4 v[214:215], off
	v_lshl_add_u64 v[214:215], v[218:219], 0, s[8:9]
	s_mov_b32 m0, s31
	s_nop 0
	global_load_lds_dwordx4 v[214:215], off
	v_lshl_add_u64 v[214:215], v[220:221], 0, s[8:9]
	s_mov_b32 m0, s33
	s_nop 0
	global_load_lds_dwordx4 v[214:215], off
	s_waitcnt vmcnt(8)
	s_waitcnt lgkmcnt(0)
	s_barrier
	s_setprio 0
	s_waitcnt lgkmcnt(0)
	v_mfma_f32_16x16x32_bf16 v[60:63], v[144:147], v[182:185], v[60:63]
	v_mfma_f32_16x16x32_bf16 v[56:59], v[152:155], v[182:185], v[56:59]
	v_mfma_f32_16x16x32_bf16 v[48:51], v[144:147], v[190:193], v[48:51]
	v_mfma_f32_16x16x32_bf16 v[40:43], v[152:155], v[190:193], v[40:43]
	v_mfma_f32_16x16x32_bf16 v[32:35], v[144:147], v[198:201], v[32:35]
	v_mfma_f32_16x16x32_bf16 v[24:27], v[152:155], v[198:201], v[24:27]
	v_mfma_f32_16x16x32_bf16 v[16:19], v[144:147], v[206:209], v[16:19]
	v_mfma_f32_16x16x32_bf16 v[8:11], v[152:155], v[206:209], v[8:11]
	v_mfma_f32_16x16x32_bf16 v[60:63], v[148:151], v[186:189], v[60:63]
	v_mfma_f32_16x16x32_bf16 v[56:59], v[156:159], v[186:189], v[56:59]
	v_mfma_f32_16x16x32_bf16 v[48:51], v[148:151], v[194:197], v[48:51]
	v_mfma_f32_16x16x32_bf16 v[40:43], v[156:159], v[194:197], v[40:43]
	v_mfma_f32_16x16x32_bf16 v[32:35], v[148:151], v[202:205], v[32:35]
	v_mfma_f32_16x16x32_bf16 v[24:27], v[156:159], v[202:205], v[24:27]
	v_mfma_f32_16x16x32_bf16 v[16:19], v[148:151], v[210:213], v[16:19]
	v_mfma_f32_16x16x32_bf16 v[8:11], v[156:159], v[210:213], v[8:11]
	s_setprio 0
	s_setprio 0
	v_mfma_f32_16x16x32_bf16 v[52:55], v[160:163], v[182:185], v[52:55]
	v_mfma_f32_16x16x32_bf16 v[44:47], v[174:177], v[182:185], v[44:47]
	v_mfma_f32_16x16x32_bf16 v[36:39], v[160:163], v[190:193], v[36:39]
	v_mfma_f32_16x16x32_bf16 v[28:31], v[174:177], v[190:193], v[28:31]
	v_mfma_f32_16x16x32_bf16 v[20:23], v[160:163], v[198:201], v[20:23]
	v_mfma_f32_16x16x32_bf16 v[12:15], v[174:177], v[198:201], v[12:15]
	v_mfma_f32_16x16x32_bf16 v[4:7], v[160:163], v[206:209], v[4:7]
	v_mfma_f32_16x16x32_bf16 v[0:3], v[174:177], v[206:209], v[0:3]
	v_mfma_f32_16x16x32_bf16 v[52:55], v[164:167], v[186:189], v[52:55]
	v_mfma_f32_16x16x32_bf16 v[44:47], v[178:181], v[186:189], v[44:47]
	v_mfma_f32_16x16x32_bf16 v[36:39], v[164:167], v[194:197], v[36:39]
	v_mfma_f32_16x16x32_bf16 v[28:31], v[178:181], v[194:197], v[28:31]
	v_mfma_f32_16x16x32_bf16 v[20:23], v[164:167], v[202:205], v[20:23]
	v_mfma_f32_16x16x32_bf16 v[12:15], v[178:181], v[202:205], v[12:15]
	v_mfma_f32_16x16x32_bf16 v[4:7], v[164:167], v[210:213], v[4:7]
	v_mfma_f32_16x16x32_bf16 v[0:3], v[178:181], v[210:213], v[0:3]
	s_setprio 0
	s_barrier
	s_add_i32 s43, s43, 2
	s_add_u32 s41, s41, 0x100
	s_addc_u32 s42, s42, 0
	s_cmp_gt_u32 s43, 41
	s_mov_b64 s[14:15], s[16:17]
